# combo5 + weight-conversion tile loop: the mid-issue vmcnt(0) moved behind the remaining 23 loads (one memory round trip per tile instead of two)
# speedup vs baseline: 1.0210x; 1.0138x over previous
.LBB0_380:
	s_and_b64 vcc, exec, s[50:51]
	s_cbranch_vccz .LBB0_537
	s_mul_i32 s6, s22, 0x4100
	s_add_i32 s41, s6, 0
	v_readlane_b32 s6, v251, 26
	s_add_i32 s38, s88, s6
	s_cmpk_gt_i32 s38, 0x15ff
	s_cbranch_scc1 .LBB0_457
	v_readlane_b32 s8, v248, 0
	s_ashr_i32 s21, s8, 31
	v_readlane_b32 s9, v248, 1
	s_mov_b32 s20, s8
	s_add_u32 s8, s90, 0x6600000
	s_addc_u32 s9, s91, 0
	s_lshl_b64 s[42:43], s[20:21], 22
	s_add_u32 s10, s90, 0x2280000
	s_addc_u32 s11, s91, 0
	s_lshl_b64 s[44:45], s[20:21], 23
	s_add_u32 s12, s90, 0x1e80000
	s_addc_u32 s13, s91, 0
	s_add_u32 s14, s90, 0x1c80000
	s_addc_u32 s15, s91, 0
	s_lshl_b64 s[46:47], s[20:21], 24
	s_add_u32 s16, s90, 0x1480000
	s_mov_b32 s18, s20
	s_addc_u32 s17, s91, 0
	v_writelane_b32 v248, s18, 0
	s_mul_hi_i32 s6, s20, 0x2630000
	s_mul_i32 s33, s20, 0x2630000
	v_writelane_b32 v248, s19, 1
	s_add_u32 s18, s90, 0xf80000
	s_addc_u32 s19, s91, 0
	v_readlane_b32 s20, v249, 19
	v_readlane_b32 s21, v249, 20
	s_add_u32 s20, s20, s42
	v_readlane_b32 s48, v249, 29
	s_addc_u32 s21, s21, s43
	v_readlane_b32 s50, v249, 31
	v_readlane_b32 s51, v249, 32
	s_add_u32 s66, s50, s44
	s_addc_u32 s67, s51, s45
	v_readlane_b32 s49, v249, 30
	s_add_u32 s44, s48, s42
	v_readlane_b32 s56, v250, 41
	s_addc_u32 s45, s49, s43
	v_readlane_b32 s62, v250, 47
	v_readlane_b32 s57, v250, 42
	v_readlane_b32 s58, v250, 43
	v_readlane_b32 s59, v250, 44
	v_readlane_b32 s60, v250, 45
	v_readlane_b32 s61, v250, 46
	v_readlane_b32 s63, v250, 48
	s_add_u32 s46, s62, s46
	v_lshlrev_b32_e32 v2, 3, v128
	s_addc_u32 s47, s63, s47
	v_readlane_b32 s48, v250, 51
	v_add_u32_e32 v4, s41, v2
	v_and_b32_e32 v2, 24, v2
	v_readlane_b32 s50, v250, 53
	v_readlane_b32 s56, v250, 59
	v_lshlrev_b32_e32 v0, 1, v128
	v_lshrrev_b32_e32 v5, 2, v128
	v_mul_u32_u24_e32 v3, 0x204, v2
	v_and_b32_e32 v6, 60, v128
	v_readlane_b32 s51, v250, 54
	v_readlane_b32 s57, v250, 60
	s_add_u32 s50, s56, s33
	v_or_b32_e32 v1, 1, v0
	v_add3_u32 v6, s41, v3, v6
	v_or_b32_e32 v7, 16, v5
	v_or_b32_e32 v8, 32, v5
	v_or_b32_e32 v9, 48, v5
	v_or_b32_e32 v10, 64, v5
	v_or_b32_e32 v11, 0x50, v5
	v_or_b32_e32 v12, 0x60, v5
	v_or_b32_e32 v13, 0x70, v5
	s_addc_u32 s51, s57, s6
	v_lshlrev_b32_e32 v2, 1, v2
	v_readlane_b32 s49, v250, 52
	v_readlane_b32 s52, v250, 55
	v_readlane_b32 s53, v250, 56
	v_readlane_b32 s54, v250, 57
	v_readlane_b32 s55, v250, 58
	v_readlane_b32 s58, v250, 61
	v_readlane_b32 s59, v250, 62
	v_readlane_b32 s60, v250, 63
	v_readlane_b32 s61, v249, 0
	v_readlane_b32 s62, v249, 1
	v_readlane_b32 s63, v249, 2
	s_waitcnt vmcnt(0)
	s_branch .LBB0_385

.LBB0_384:
	s_lshl_b32 s60, s64, 5
	s_ashr_i32 s61, s60, 31
	s_lshl_b32 s33, s43, 6
	s_mul_i32 s43, s6, s61
	s_mul_hi_u32 s64, s6, s60
	s_add_i32 s65, s64, s43
	s_mul_i32 s64, s6, s60
	s_lshl_b64 s[64:65], s[64:65], 2
	s_add_u32 s58, s58, s64
	s_addc_u32 s59, s59, s65
	s_ashr_i32 s43, s42, 31
	s_lshl_b64 s[42:43], s[42:43], 2
	s_add_u32 s42, s58, s42
	s_addc_u32 s43, s59, s43
	v_lshlrev_b32_e32 v176, 2, v0
	v_lshl_add_u64 v[14:15], s[42:43], 0, v[176:177]
	global_load_dwordx2 v[16:17], v176, s[42:43] nt
	s_lshl_b32 s42, s6, 1
	s_mov_b32 s43, s7
	v_lshl_add_u64 v[20:21], s[42:43], 2, v[14:15]
	s_mul_i32 s42, s6, 3
	v_lshl_add_u64 v[22:23], s[42:43], 2, v[14:15]
	s_lshl_b32 s42, s6, 2
	v_lshl_add_u64 v[24:25], s[42:43], 2, v[14:15]
	s_mul_i32 s42, s6, 5
	v_lshl_add_u64 v[26:27], s[42:43], 2, v[14:15]
	s_mul_i32 s42, s6, 6
	v_lshl_add_u64 v[28:29], s[42:43], 2, v[14:15]
	s_mul_i32 s42, s6, 7
	v_lshl_add_u64 v[30:31], s[42:43], 2, v[14:15]
	s_lshl_b32 s42, s6, 3
	v_lshl_add_u64 v[32:33], s[42:43], 2, v[14:15]
	s_mul_i32 s42, s6, 9
	v_lshl_add_u64 v[34:35], s[42:43], 2, v[14:15]
	s_mul_i32 s42, s6, 10
	v_lshl_add_u64 v[18:19], s[6:7], 2, v[14:15]
	v_lshl_add_u64 v[36:37], s[42:43], 2, v[14:15]
	s_mul_i32 s42, s6, 11
	global_load_dwordx2 v[18:19], v[18:19], off nt
	s_nop 0
	global_load_dwordx2 v[20:21], v[20:21], off nt
	s_nop 0
	global_load_dwordx2 v[22:23], v[22:23], off nt
	s_nop 0
	global_load_dwordx2 v[24:25], v[24:25], off nt
	v_lshl_add_u64 v[38:39], s[42:43], 2, v[14:15]
	s_mul_i32 s42, s6, 12
	v_lshl_add_u64 v[40:41], s[42:43], 2, v[14:15]
	s_mul_i32 s42, s6, 13
	v_lshl_add_u64 v[42:43], s[42:43], 2, v[14:15]
	s_mul_i32 s42, s6, 14
	global_load_dwordx2 v[26:27], v[26:27], off nt
	s_nop 0
	global_load_dwordx2 v[28:29], v[28:29], off nt
	s_nop 0
	global_load_dwordx2 v[30:31], v[30:31], off nt
	s_nop 0
	global_load_dwordx2 v[32:33], v[32:33], off nt
	v_lshl_add_u64 v[44:45], s[42:43], 2, v[14:15]
	s_mul_i32 s42, s6, 15
	v_lshl_add_u64 v[46:47], s[42:43], 2, v[14:15]
	s_lshl_b32 s42, s6, 4
	v_lshl_add_u64 v[48:49], s[42:43], 2, v[14:15]
	s_mul_i32 s42, s6, 17
	global_load_dwordx2 v[34:35], v[34:35], off nt
	s_nop 0
	global_load_dwordx2 v[36:37], v[36:37], off nt
	s_nop 0
	global_load_dwordx2 v[38:39], v[38:39], off nt
	s_nop 0
	global_load_dwordx2 v[40:41], v[40:41], off nt
	v_lshl_add_u64 v[50:51], s[42:43], 2, v[14:15]
	s_mul_i32 s42, s6, 18
	v_lshl_add_u64 v[52:53], s[42:43], 2, v[14:15]
	s_mul_i32 s42, s6, 19
	v_lshl_add_u64 v[54:55], s[42:43], 2, v[14:15]
	s_mul_i32 s42, s6, 20
	global_load_dwordx2 v[42:43], v[42:43], off nt
	s_nop 0
	global_load_dwordx2 v[44:45], v[44:45], off nt
	s_nop 0
	global_load_dwordx2 v[46:47], v[46:47], off nt
	s_nop 0
	global_load_dwordx2 v[48:49], v[48:49], off nt
	v_lshl_add_u64 v[56:57], s[42:43], 2, v[14:15]
	s_mul_i32 s42, s6, 21
	v_lshl_add_u64 v[58:59], s[42:43], 2, v[14:15]
	s_mul_i32 s42, s6, 22
	v_lshl_add_u64 v[60:61], s[42:43], 2, v[14:15]
	s_mul_i32 s42, s6, 23
	global_load_dwordx2 v[50:51], v[50:51], off nt
	s_nop 0
	global_load_dwordx2 v[52:53], v[52:53], off nt
	s_nop 0
	global_load_dwordx2 v[54:55], v[54:55], off nt
	s_nop 0
	global_load_dwordx2 v[56:57], v[56:57], off nt
	v_lshl_add_u64 v[62:63], s[42:43], 2, v[14:15]
	s_mul_i32 s42, s6, 24
	s_waitcnt lgkmcnt(0)
	v_lshl_add_u64 v[64:65], s[42:43], 2, v[14:15]
	s_mul_i32 s42, s6, 25
	v_lshl_add_u64 v[66:67], s[42:43], 2, v[14:15]
	s_mul_i32 s42, s6, 26
	global_load_dwordx2 v[58:59], v[58:59], off nt
	s_nop 0
	global_load_dwordx2 v[60:61], v[60:61], off nt
	s_nop 0
	global_load_dwordx2 v[62:63], v[62:63], off nt
	s_nop 0
	global_load_dwordx2 v[64:65], v[64:65], off nt
	v_lshl_add_u64 v[68:69], s[42:43], 2, v[14:15]
	s_mul_i32 s42, s6, 27
	v_lshl_add_u64 v[70:71], s[42:43], 2, v[14:15]
	s_mul_i32 s42, s6, 28
	v_lshl_add_u64 v[72:73], s[42:43], 2, v[14:15]
	s_mul_i32 s42, s6, 29
	global_load_dwordx2 v[66:67], v[66:67], off nt
	s_nop 0
	global_load_dwordx2 v[68:69], v[68:69], off nt
	s_nop 0
	global_load_dwordx2 v[70:71], v[70:71], off nt
	s_nop 0
	global_load_dwordx2 v[72:73], v[72:73], off nt
	v_lshl_add_u64 v[74:75], s[42:43], 2, v[14:15]
	s_mul_i32 s42, s6, 30
	s_mul_i32 s6, s6, 31
	v_lshl_add_u64 v[76:77], s[42:43], 2, v[14:15]
	v_lshl_add_u64 v[14:15], s[6:7], 2, v[14:15]
	global_load_dwordx2 v[74:75], v[74:75], off nt
	s_nop 0
	global_load_dwordx2 v[76:77], v[76:77], off nt
	s_nop 0
	global_load_dwordx2 v[14:15], v[14:15], off nt
	v_cmp_gt_u32_e32 vcc, s39, v0
	v_cmp_gt_u32_e64 s[42:43], s39, v1
	s_waitcnt vmcnt(0)
	v_cndmask_b32_e32 v16, 0, v16, vcc
	v_cndmask_b32_e64 v17, 0, v17, s[42:43]
	v_cndmask_b32_e32 v3, 0, v18, vcc
	v_cndmask_b32_e64 v18, 0, v19, s[42:43]
	ds_write2_b32 v4, v3, v18 offset0:129 offset1:130
	v_cndmask_b32_e32 v18, 0, v20, vcc
	v_cndmask_b32_e64 v19, 0, v21, s[42:43]
	ds_write2_b64 v4, v[16:17], v[18:19] offset1:129
	v_cndmask_b32_e32 v3, 0, v22, vcc
	v_add_u32_e32 v16, 0x60c, v4
	v_cndmask_b32_e64 v17, 0, v23, s[42:43]
	ds_write2_b32 v16, v3, v17 offset1:1
	v_cndmask_b32_e32 v3, 0, v26, vcc
	v_add_u32_e32 v18, 0xa14, v4
	v_cndmask_b32_e64 v19, 0, v27, s[42:43]
	v_cndmask_b32_e32 v16, 0, v24, vcc
	v_cndmask_b32_e64 v17, 0, v25, s[42:43]
	ds_write2_b32 v18, v3, v19 offset1:1
	v_cndmask_b32_e32 v18, 0, v28, vcc
	v_cndmask_b32_e64 v19, 0, v29, s[42:43]
	v_add_u32_e32 v3, 0x800, v4
	ds_write2_b64 v3, v[16:17], v[18:19] offset0:2 offset1:131
	v_cndmask_b32_e32 v3, 0, v30, vcc
	v_add_u32_e32 v16, 0xe1c, v4
	v_cndmask_b32_e64 v17, 0, v31, s[42:43]
	ds_write2_b32 v16, v3, v17 offset1:1
	v_cndmask_b32_e32 v3, 0, v34, vcc
	v_add_u32_e32 v18, 0x1224, v4
	v_cndmask_b32_e64 v19, 0, v35, s[42:43]
	v_cndmask_b32_e32 v16, 0, v32, vcc
	v_cndmask_b32_e64 v17, 0, v33, s[42:43]
	ds_write2_b32 v18, v3, v19 offset1:1
	v_cndmask_b32_e32 v18, 0, v36, vcc
	v_cndmask_b32_e64 v19, 0, v37, s[42:43]
	v_add_u32_e32 v3, 0x1000, v4
	ds_write2_b64 v3, v[16:17], v[18:19] offset0:4 offset1:133
	v_cndmask_b32_e32 v3, 0, v38, vcc
	v_add_u32_e32 v16, 0x162c, v4
	v_cndmask_b32_e64 v17, 0, v39, s[42:43]
	ds_write2_b32 v16, v3, v17 offset1:1
	v_cndmask_b32_e32 v3, 0, v42, vcc
	v_add_u32_e32 v18, 0x1a34, v4
	v_cndmask_b32_e64 v19, 0, v43, s[42:43]
	v_cndmask_b32_e32 v16, 0, v40, vcc
	v_cndmask_b32_e64 v17, 0, v41, s[42:43]
	ds_write2_b32 v18, v3, v19 offset1:1
	v_cndmask_b32_e32 v18, 0, v44, vcc
	v_cndmask_b32_e64 v19, 0, v45, s[42:43]
	v_add_u32_e32 v3, 0x1800, v4
	ds_write2_b64 v3, v[16:17], v[18:19] offset0:6 offset1:135
	v_cndmask_b32_e32 v3, 0, v46, vcc
	v_add_u32_e32 v16, 0x1e3c, v4
	v_cndmask_b32_e64 v17, 0, v47, s[42:43]
	ds_write2_b32 v16, v3, v17 offset1:1
	v_cndmask_b32_e32 v3, 0, v50, vcc
	v_add_u32_e32 v18, 0x2244, v4
	v_cndmask_b32_e64 v19, 0, v51, s[42:43]
	v_cndmask_b32_e32 v16, 0, v48, vcc
	v_cndmask_b32_e64 v17, 0, v49, s[42:43]
	ds_write2_b32 v18, v3, v19 offset1:1
	v_cndmask_b32_e32 v18, 0, v52, vcc
	v_cndmask_b32_e64 v19, 0, v53, s[42:43]
	v_add_u32_e32 v3, 0x2000, v4
	ds_write2_b64 v3, v[16:17], v[18:19] offset0:8 offset1:137
	v_cndmask_b32_e32 v3, 0, v54, vcc
	v_add_u32_e32 v16, 0x264c, v4
	v_cndmask_b32_e64 v17, 0, v55, s[42:43]
	ds_write2_b32 v16, v3, v17 offset1:1
	v_cndmask_b32_e32 v3, 0, v58, vcc
	v_add_u32_e32 v18, 0x2a54, v4
	v_cndmask_b32_e64 v19, 0, v59, s[42:43]
	v_cndmask_b32_e32 v16, 0, v56, vcc
	v_cndmask_b32_e64 v17, 0, v57, s[42:43]
	ds_write2_b32 v18, v3, v19 offset1:1
	v_cndmask_b32_e32 v18, 0, v60, vcc
	v_cndmask_b32_e64 v19, 0, v61, s[42:43]
	v_add_u32_e32 v3, 0x2800, v4
	ds_write2_b64 v3, v[16:17], v[18:19] offset0:10 offset1:139
	v_cndmask_b32_e32 v3, 0, v62, vcc
	v_add_u32_e32 v16, 0x2e5c, v4
	v_cndmask_b32_e64 v17, 0, v63, s[42:43]
	ds_write2_b32 v16, v3, v17 offset1:1
	v_cndmask_b32_e32 v3, 0, v66, vcc
	v_add_u32_e32 v18, 0x3264, v4
	v_cndmask_b32_e64 v19, 0, v67, s[42:43]
	v_cndmask_b32_e32 v16, 0, v64, vcc
	v_cndmask_b32_e64 v17, 0, v65, s[42:43]
	ds_write2_b32 v18, v3, v19 offset1:1
	v_cndmask_b32_e32 v18, 0, v68, vcc
	v_cndmask_b32_e64 v19, 0, v69, s[42:43]
	v_add_u32_e32 v3, 0x3000, v4
	ds_write2_b64 v3, v[16:17], v[18:19] offset0:12 offset1:141
	v_cndmask_b32_e32 v3, 0, v70, vcc
	v_add_u32_e32 v16, 0x366c, v4
	v_cndmask_b32_e64 v17, 0, v71, s[42:43]
	ds_write2_b32 v16, v3, v17 offset1:1
	v_cndmask_b32_e32 v3, 0, v74, vcc
	v_add_u32_e32 v18, 0x3a74, v4
	v_cndmask_b32_e64 v19, 0, v75, s[42:43]
	v_cndmask_b32_e32 v16, 0, v72, vcc
	v_cndmask_b32_e64 v17, 0, v73, s[42:43]
	ds_write2_b32 v18, v3, v19 offset1:1
	v_cndmask_b32_e32 v18, 0, v76, vcc
	v_cndmask_b32_e64 v19, 0, v77, s[42:43]
	v_add_u32_e32 v3, 0x3800, v4
	ds_write2_b64 v3, v[16:17], v[18:19] offset0:14 offset1:143
	v_cndmask_b32_e32 v3, 0, v14, vcc
	v_add_u32_e32 v14, 0x3e7c, v4
	v_cndmask_b32_e64 v15, 0, v15, s[42:43]
	ds_write2_b32 v14, v3, v15 offset1:1
	ds_read_b32 v14, v6
	ds_read_b32 v15, v6 offset:516
	ds_read_b32 v16, v6 offset:1032
	ds_read_b32 v17, v6 offset:1548
	ds_read_b32 v20, v6 offset:2064
	ds_read_b32 v21, v6 offset:2580
	ds_read_b32 v22, v6 offset:3096
	ds_read_b32 v23, v6 offset:3612
	s_lshl_b64 s[42:43], s[60:61], 1
	s_add_u32 s42, s56, s42
	s_addc_u32 s43, s57, s43
	v_mov_b32_e32 v3, v177
	v_lshl_add_u64 v[18:19], s[42:43], 0, v[2:3]
	v_or_b32_e32 v3, s33, v5
	s_ashr_i32 s6, s33, 31
	s_waitcnt lgkmcnt(0)
	v_cvt_pk_bf16_f32 v14, v14, v15
	v_cvt_pk_bf16_f32 v15, v16, v17
	v_cvt_pk_bf16_f32 v16, v20, v21
	v_cvt_pk_bf16_f32 v17, v22, v23
	s_mul_i32 s6, s54, s6
	v_mul_lo_u32 v22, s55, v3
	v_mad_u64_u32 v[20:21], s[42:43], s54, v3, 0
	v_add3_u32 v21, v21, s6, v22
	v_lshl_add_u64 v[20:21], v[20:21], 1, v[18:19]
	flat_store_dwordx4 v[20:21], v[14:17]
	ds_read_b32 v3, v6 offset:64
	ds_read_b32 v14, v6 offset:580
	ds_read_b32 v15, v6 offset:1096
	ds_read_b32 v16, v6 offset:1612
	ds_read_b32 v17, v6 offset:2128
	ds_read_b32 v20, v6 offset:2644
	ds_read_b32 v21, v6 offset:3160
	ds_read_b32 v22, v6 offset:3676
	s_waitcnt lgkmcnt(0)
	v_cvt_pk_bf16_f32 v14, v3, v14
	v_or_b32_e32 v3, s33, v7
	v_cvt_pk_bf16_f32 v15, v15, v16
	v_cvt_pk_bf16_f32 v16, v17, v20
	v_cvt_pk_bf16_f32 v17, v21, v22
	v_mul_lo_u32 v22, s55, v3
	v_mad_u64_u32 v[20:21], s[42:43], s54, v3, 0
	v_add3_u32 v21, v21, s6, v22
	v_lshl_add_u64 v[20:21], v[20:21], 1, v[18:19]
	flat_store_dwordx4 v[20:21], v[14:17]
	ds_read_b32 v3, v6 offset:128
	ds_read_b32 v14, v6 offset:644
	ds_read_b32 v15, v6 offset:1160
	ds_read_b32 v16, v6 offset:1676
	ds_read_b32 v17, v6 offset:2192
	ds_read_b32 v20, v6 offset:2708
	ds_read_b32 v21, v6 offset:3224
	ds_read_b32 v22, v6 offset:3740
	s_waitcnt lgkmcnt(0)
	v_cvt_pk_bf16_f32 v14, v3, v14
	v_or_b32_e32 v3, s33, v8
	v_cvt_pk_bf16_f32 v15, v15, v16
	v_cvt_pk_bf16_f32 v16, v17, v20
	v_cvt_pk_bf16_f32 v17, v21, v22
	v_mul_lo_u32 v22, s55, v3
	v_mad_u64_u32 v[20:21], s[42:43], s54, v3, 0
	v_add3_u32 v21, v21, s6, v22
	v_lshl_add_u64 v[20:21], v[20:21], 1, v[18:19]
	flat_store_dwordx4 v[20:21], v[14:17]
	ds_read_b32 v3, v6 offset:192
	ds_read_b32 v14, v6 offset:708
	ds_read_b32 v15, v6 offset:1224
	ds_read_b32 v16, v6 offset:1740
	ds_read_b32 v17, v6 offset:2256
	ds_read_b32 v20, v6 offset:2772
	ds_read_b32 v21, v6 offset:3288
	ds_read_b32 v22, v6 offset:3804
	s_waitcnt lgkmcnt(0)
	v_cvt_pk_bf16_f32 v14, v3, v14
	v_or_b32_e32 v3, s33, v9
	v_cvt_pk_bf16_f32 v15, v15, v16
	v_cvt_pk_bf16_f32 v16, v17, v20
	v_cvt_pk_bf16_f32 v17, v21, v22
	v_mul_lo_u32 v22, s55, v3
	v_mad_u64_u32 v[20:21], s[42:43], s54, v3, 0
	v_add3_u32 v21, v21, s6, v22
	v_lshl_add_u64 v[20:21], v[20:21], 1, v[18:19]
	flat_store_dwordx4 v[20:21], v[14:17]
	ds_read_b32 v3, v6 offset:256
	ds_read_b32 v14, v6 offset:772
	ds_read_b32 v15, v6 offset:1288
	ds_read_b32 v16, v6 offset:1804
	ds_read_b32 v17, v6 offset:2320
	ds_read_b32 v20, v6 offset:2836
	ds_read_b32 v21, v6 offset:3352
	ds_read_b32 v22, v6 offset:3868
	s_waitcnt lgkmcnt(0)
	v_cvt_pk_bf16_f32 v14, v3, v14
	v_or_b32_e32 v3, s33, v10
	v_cvt_pk_bf16_f32 v15, v15, v16
	v_cvt_pk_bf16_f32 v16, v17, v20
	v_cvt_pk_bf16_f32 v17, v21, v22
	v_mul_lo_u32 v22, s55, v3
	v_mad_u64_u32 v[20:21], s[42:43], s54, v3, 0
	v_add3_u32 v21, v21, s6, v22
	v_lshl_add_u64 v[20:21], v[20:21], 1, v[18:19]
	flat_store_dwordx4 v[20:21], v[14:17]
	ds_read_b32 v3, v6 offset:320
	ds_read_b32 v14, v6 offset:836
	ds_read_b32 v15, v6 offset:1352
	ds_read_b32 v16, v6 offset:1868
	ds_read_b32 v17, v6 offset:2384
	ds_read_b32 v20, v6 offset:2900
	ds_read_b32 v21, v6 offset:3416
	ds_read_b32 v22, v6 offset:3932
	s_waitcnt lgkmcnt(0)
	v_cvt_pk_bf16_f32 v14, v3, v14
	v_or_b32_e32 v3, s33, v11
	v_cvt_pk_bf16_f32 v15, v15, v16
	v_cvt_pk_bf16_f32 v16, v17, v20
	v_cvt_pk_bf16_f32 v17, v21, v22
	v_mul_lo_u32 v22, s55, v3
	v_mad_u64_u32 v[20:21], s[42:43], s54, v3, 0
	v_add3_u32 v21, v21, s6, v22
	v_lshl_add_u64 v[20:21], v[20:21], 1, v[18:19]
	flat_store_dwordx4 v[20:21], v[14:17]
	ds_read_b32 v3, v6 offset:384
	ds_read_b32 v14, v6 offset:900
	ds_read_b32 v15, v6 offset:1416
	ds_read_b32 v16, v6 offset:1932
	ds_read_b32 v17, v6 offset:2448
	ds_read_b32 v20, v6 offset:2964
	ds_read_b32 v21, v6 offset:3480
	ds_read_b32 v22, v6 offset:3996
	s_waitcnt lgkmcnt(0)
	v_cvt_pk_bf16_f32 v14, v3, v14
	v_or_b32_e32 v3, s33, v12
	v_cvt_pk_bf16_f32 v15, v15, v16
	v_cvt_pk_bf16_f32 v16, v17, v20
	v_cvt_pk_bf16_f32 v17, v21, v22
	v_mul_lo_u32 v22, s55, v3
	v_mad_u64_u32 v[20:21], s[42:43], s54, v3, 0
	v_add3_u32 v21, v21, s6, v22
	v_lshl_add_u64 v[20:21], v[20:21], 1, v[18:19]
	flat_store_dwordx4 v[20:21], v[14:17]
	ds_read_b32 v3, v6 offset:448
	ds_read_b32 v14, v6 offset:964
	ds_read_b32 v15, v6 offset:1480
	ds_read_b32 v16, v6 offset:1996
	ds_read_b32 v17, v6 offset:2512
	ds_read_b32 v20, v6 offset:3028
	ds_read_b32 v21, v6 offset:3544
	ds_read_b32 v22, v6 offset:4060
	s_waitcnt lgkmcnt(0)
	v_cvt_pk_bf16_f32 v14, v3, v14
	v_or_b32_e32 v3, s33, v13
	v_cvt_pk_bf16_f32 v15, v15, v16
	v_cvt_pk_bf16_f32 v16, v17, v20
	v_cvt_pk_bf16_f32 v17, v21, v22
	v_mul_lo_u32 v22, s55, v3
	v_mad_u64_u32 v[20:21], s[42:43], s54, v3, 0
	v_add3_u32 v21, v21, s6, v22
	s_add_i32 s38, s38, s36
	v_lshl_add_u64 v[18:19], v[20:21], 1, v[18:19]
	s_cmpk_lt_i32 s38, 0x1600
	flat_store_dwordx4 v[18:19], v[14:17]
	s_cbranch_scc0 .LBB0_457

.LBB0_457:
	s_cmpk_lt_i32 s88, 0xb00
	v_readlane_b32 s10, v251, 24
	s_cselect_b64 s[8:9], -1, 0
	v_readlane_b32 s11, v251, 25
	s_and_b64 s[8:9], s[10:11], s[8:9]
	s_andn2_b64 vcc, exec, s[8:9]
	s_cbranch_vccnz .LBB0_537
	v_readlane_b32 s8, v248, 0
	s_ashr_i32 s39, s8, 31
	v_readlane_b32 s9, v248, 1
	s_mov_b32 s38, s8
	s_mul_hi_i32 s76, s8, 0x2c00000
	s_mul_i32 s80, s8, 0x2c00000
	s_add_u32 s8, s90, 0x1eca4000
	s_addc_u32 s9, s91, 0
	s_add_u32 s10, s90, 0x6600000
	s_addc_u32 s11, s91, 0
	s_lshl_b64 s[42:43], s[38:39], 22
	s_add_u32 s12, s90, 0x2280000
	s_addc_u32 s13, s91, 0
	s_lshl_b64 s[46:47], s[38:39], 23
	s_add_u32 s14, s90, 0x1e80000
	s_addc_u32 s15, s91, 0
	s_add_u32 s16, s90, 0x1c80000
	v_writelane_b32 v248, s8, 4
	s_addc_u32 s17, s91, 0
	s_lshl_b64 s[54:55], s[38:39], 24
	v_writelane_b32 v248, s9, 5
	s_add_u32 s18, s90, 0x1480000
	s_mov_b32 s20, s38
	s_addc_u32 s19, s91, 0
	v_writelane_b32 v248, s20, 0
	s_mul_hi_i32 s6, s38, 0x2630000
	s_mul_i32 s33, s38, 0x2630000
	v_writelane_b32 v248, s21, 1
	s_add_u32 s20, s90, 0xf80000
	s_addc_u32 s21, s91, 0
	v_readlane_b32 s38, v249, 23
	v_readlane_b32 s39, v249, 24
	s_add_u32 s66, s38, s80
	s_addc_u32 s67, s39, s76
	v_readlane_b32 s38, v249, 19
	v_readlane_b32 s39, v249, 20
	s_add_u32 s8, s38, s42
	v_readlane_b32 s48, v249, 29
	s_addc_u32 s9, s39, s43
	v_readlane_b32 s50, v249, 31
	v_readlane_b32 s51, v249, 32
	s_add_u32 s92, s50, s46
	s_addc_u32 s93, s51, s47
	v_readlane_b32 s49, v249, 30
	s_add_u32 s94, s48, s42
	v_readlane_b32 s56, v250, 41
	s_addc_u32 s95, s49, s43
	v_readlane_b32 s62, v250, 47
	v_readlane_b32 s57, v250, 42
	v_readlane_b32 s58, v250, 43
	v_readlane_b32 s59, v250, 44
	v_readlane_b32 s63, v250, 48
	s_add_u32 s38, s62, s54
	s_addc_u32 s39, s63, s55
	v_readlane_b32 s44, v250, 51
	v_lshlrev_b32_e32 v2, 3, v128
	v_readlane_b32 s52, v250, 59
	v_readlane_b32 s56, v250, 63
	v_add_u32_e32 v4, s41, v2
	v_and_b32_e32 v2, 24, v2
	v_readlane_b32 s53, v250, 60
	v_readlane_b32 s57, v249, 0
	s_add_u32 s56, s52, s33
	v_lshlrev_b32_e32 v0, 1, v128
	v_lshrrev_b32_e32 v5, 2, v128
	v_mul_u32_u24_e32 v3, 0x204, v2
	v_and_b32_e32 v6, 60, v128
	s_addc_u32 s57, s53, s6
	v_readlane_b32 s6, v249, 16
	v_or_b32_e32 v1, 1, v0
	v_add3_u32 v6, s41, v3, v6
	v_or_b32_e32 v7, 16, v5
	v_or_b32_e32 v8, 32, v5
	v_or_b32_e32 v9, 48, v5
	v_or_b32_e32 v10, 64, v5
	v_or_b32_e32 v11, 0x50, v5
	v_or_b32_e32 v12, 0x60, v5
	v_or_b32_e32 v13, 0x70, v5
	s_add_i32 s41, s6, s22
	v_lshlrev_b32_e32 v2, 1, v2
	v_readlane_b32 s60, v250, 45
	v_readlane_b32 s61, v250, 46
	v_readlane_b32 s45, v250, 52
	v_readlane_b32 s46, v250, 53
	v_readlane_b32 s47, v250, 54
	v_readlane_b32 s48, v250, 55
	v_readlane_b32 s49, v250, 56
	v_readlane_b32 s50, v250, 57
	v_readlane_b32 s51, v250, 58
	v_readlane_b32 s54, v250, 61
	v_readlane_b32 s55, v250, 62
	v_readlane_b32 s58, v249, 1
	v_readlane_b32 s59, v249, 2
	s_waitcnt vmcnt(0)
	s_branch .LBB0_461

.LBB0_460:
	s_lshl_b32 s64, s71, 5
	s_ashr_i32 s65, s64, 31
	s_lshl_b32 s33, s69, 6
	s_mul_i32 s43, s6, s65
	s_mul_hi_u32 s69, s6, s64
	s_add_i32 s73, s69, s43
	s_mul_i32 s72, s6, s64
	s_lshl_b64 s[72:73], s[72:73], 2
	s_add_u32 s62, s62, s72
	s_addc_u32 s63, s63, s73
	s_ashr_i32 s43, s42, 31
	s_lshl_b64 s[42:43], s[42:43], 2
	s_add_u32 s42, s62, s42
	s_addc_u32 s43, s63, s43
	v_lshlrev_b32_e32 v176, 2, v0
	v_lshl_add_u64 v[14:15], s[42:43], 0, v[176:177]
	global_load_dwordx2 v[16:17], v176, s[42:43] nt
	s_lshl_b32 s42, s6, 1
	s_mov_b32 s43, s7
	v_lshl_add_u64 v[20:21], s[42:43], 2, v[14:15]
	s_mul_i32 s42, s6, 3
	v_lshl_add_u64 v[22:23], s[42:43], 2, v[14:15]
	s_lshl_b32 s42, s6, 2
	v_lshl_add_u64 v[24:25], s[42:43], 2, v[14:15]
	s_mul_i32 s42, s6, 5
	v_lshl_add_u64 v[26:27], s[42:43], 2, v[14:15]
	s_mul_i32 s42, s6, 6
	v_lshl_add_u64 v[28:29], s[42:43], 2, v[14:15]
	s_mul_i32 s42, s6, 7
	v_lshl_add_u64 v[30:31], s[42:43], 2, v[14:15]
	s_lshl_b32 s42, s6, 3
	v_lshl_add_u64 v[32:33], s[42:43], 2, v[14:15]
	s_mul_i32 s42, s6, 9
	v_lshl_add_u64 v[34:35], s[42:43], 2, v[14:15]
	s_mul_i32 s42, s6, 10
	v_lshl_add_u64 v[18:19], s[6:7], 2, v[14:15]
	v_lshl_add_u64 v[36:37], s[42:43], 2, v[14:15]
	s_mul_i32 s42, s6, 11
	global_load_dwordx2 v[18:19], v[18:19], off nt
	s_nop 0
	global_load_dwordx2 v[20:21], v[20:21], off nt
	s_nop 0
	global_load_dwordx2 v[22:23], v[22:23], off nt
	s_nop 0
	global_load_dwordx2 v[24:25], v[24:25], off nt
	v_lshl_add_u64 v[38:39], s[42:43], 2, v[14:15]
	s_mul_i32 s42, s6, 12
	v_lshl_add_u64 v[40:41], s[42:43], 2, v[14:15]
	s_mul_i32 s42, s6, 13
	v_lshl_add_u64 v[42:43], s[42:43], 2, v[14:15]
	s_mul_i32 s42, s6, 14
	global_load_dwordx2 v[26:27], v[26:27], off nt
	s_nop 0
	global_load_dwordx2 v[28:29], v[28:29], off nt
	s_nop 0
	global_load_dwordx2 v[30:31], v[30:31], off nt
	s_nop 0
	global_load_dwordx2 v[32:33], v[32:33], off nt
	v_lshl_add_u64 v[44:45], s[42:43], 2, v[14:15]
	s_mul_i32 s42, s6, 15
	v_lshl_add_u64 v[46:47], s[42:43], 2, v[14:15]
	s_lshl_b32 s42, s6, 4
	v_lshl_add_u64 v[48:49], s[42:43], 2, v[14:15]
	s_mul_i32 s42, s6, 17
	global_load_dwordx2 v[34:35], v[34:35], off nt
	s_nop 0
	global_load_dwordx2 v[36:37], v[36:37], off nt
	s_nop 0
	global_load_dwordx2 v[38:39], v[38:39], off nt
	s_nop 0
	global_load_dwordx2 v[40:41], v[40:41], off nt
	v_lshl_add_u64 v[50:51], s[42:43], 2, v[14:15]
	s_mul_i32 s42, s6, 18
	v_lshl_add_u64 v[52:53], s[42:43], 2, v[14:15]
	s_mul_i32 s42, s6, 19
	v_lshl_add_u64 v[54:55], s[42:43], 2, v[14:15]
	s_mul_i32 s42, s6, 20
	global_load_dwordx2 v[42:43], v[42:43], off nt
	s_nop 0
	global_load_dwordx2 v[44:45], v[44:45], off nt
	s_nop 0
	global_load_dwordx2 v[46:47], v[46:47], off nt
	s_nop 0
	global_load_dwordx2 v[48:49], v[48:49], off nt
	v_lshl_add_u64 v[56:57], s[42:43], 2, v[14:15]
	s_mul_i32 s42, s6, 21
	v_lshl_add_u64 v[58:59], s[42:43], 2, v[14:15]
	s_mul_i32 s42, s6, 22
	v_lshl_add_u64 v[60:61], s[42:43], 2, v[14:15]
	s_mul_i32 s42, s6, 23
	global_load_dwordx2 v[50:51], v[50:51], off nt
	s_nop 0
	global_load_dwordx2 v[52:53], v[52:53], off nt
	s_nop 0
	global_load_dwordx2 v[54:55], v[54:55], off nt
	s_nop 0
	global_load_dwordx2 v[56:57], v[56:57], off nt
	v_lshl_add_u64 v[62:63], s[42:43], 2, v[14:15]
	s_mul_i32 s42, s6, 24
	s_waitcnt lgkmcnt(0)
	v_lshl_add_u64 v[64:65], s[42:43], 2, v[14:15]
	s_mul_i32 s42, s6, 25
	v_lshl_add_u64 v[66:67], s[42:43], 2, v[14:15]
	s_mul_i32 s42, s6, 26
	global_load_dwordx2 v[58:59], v[58:59], off nt
	s_nop 0
	global_load_dwordx2 v[60:61], v[60:61], off nt
	s_nop 0
	global_load_dwordx2 v[62:63], v[62:63], off nt
	s_nop 0
	global_load_dwordx2 v[64:65], v[64:65], off nt
	v_lshl_add_u64 v[68:69], s[42:43], 2, v[14:15]
	s_mul_i32 s42, s6, 27
	v_lshl_add_u64 v[70:71], s[42:43], 2, v[14:15]
	s_mul_i32 s42, s6, 28
	v_lshl_add_u64 v[72:73], s[42:43], 2, v[14:15]
	s_mul_i32 s42, s6, 29
	global_load_dwordx2 v[66:67], v[66:67], off nt
	s_nop 0
	global_load_dwordx2 v[68:69], v[68:69], off nt
	s_nop 0
	global_load_dwordx2 v[70:71], v[70:71], off nt
	s_nop 0
	global_load_dwordx2 v[72:73], v[72:73], off nt
	v_lshl_add_u64 v[74:75], s[42:43], 2, v[14:15]
	s_mul_i32 s42, s6, 30
	s_mul_i32 s6, s6, 31
	v_lshl_add_u64 v[76:77], s[42:43], 2, v[14:15]
	v_lshl_add_u64 v[14:15], s[6:7], 2, v[14:15]
	global_load_dwordx2 v[74:75], v[74:75], off nt
	s_nop 0
	global_load_dwordx2 v[76:77], v[76:77], off nt
	s_nop 0
	global_load_dwordx2 v[14:15], v[14:15], off nt
	v_cmp_gt_u32_e32 vcc, s68, v0
	v_cmp_gt_u32_e64 s[42:43], s68, v1
	s_waitcnt vmcnt(0)
	v_cndmask_b32_e32 v16, 0, v16, vcc
	v_cndmask_b32_e64 v17, 0, v17, s[42:43]
	v_cndmask_b32_e32 v3, 0, v18, vcc
	v_cndmask_b32_e64 v18, 0, v19, s[42:43]
	ds_write2_b32 v4, v3, v18 offset0:129 offset1:130
	v_cndmask_b32_e32 v18, 0, v20, vcc
	v_cndmask_b32_e64 v19, 0, v21, s[42:43]
	ds_write2_b64 v4, v[16:17], v[18:19] offset1:129
	v_cndmask_b32_e32 v3, 0, v22, vcc
	v_add_u32_e32 v16, 0x60c, v4
	v_cndmask_b32_e64 v17, 0, v23, s[42:43]
	ds_write2_b32 v16, v3, v17 offset1:1
	v_cndmask_b32_e32 v3, 0, v26, vcc
	v_add_u32_e32 v18, 0xa14, v4
	v_cndmask_b32_e64 v19, 0, v27, s[42:43]
	v_cndmask_b32_e32 v16, 0, v24, vcc
	v_cndmask_b32_e64 v17, 0, v25, s[42:43]
	ds_write2_b32 v18, v3, v19 offset1:1
	v_cndmask_b32_e32 v18, 0, v28, vcc
	v_cndmask_b32_e64 v19, 0, v29, s[42:43]
	v_add_u32_e32 v3, 0x800, v4
	ds_write2_b64 v3, v[16:17], v[18:19] offset0:2 offset1:131
	v_cndmask_b32_e32 v3, 0, v30, vcc
	v_add_u32_e32 v16, 0xe1c, v4
	v_cndmask_b32_e64 v17, 0, v31, s[42:43]
	ds_write2_b32 v16, v3, v17 offset1:1
	v_cndmask_b32_e32 v3, 0, v34, vcc
	v_add_u32_e32 v18, 0x1224, v4
	v_cndmask_b32_e64 v19, 0, v35, s[42:43]
	v_cndmask_b32_e32 v16, 0, v32, vcc
	v_cndmask_b32_e64 v17, 0, v33, s[42:43]
	ds_write2_b32 v18, v3, v19 offset1:1
	v_cndmask_b32_e32 v18, 0, v36, vcc
	v_cndmask_b32_e64 v19, 0, v37, s[42:43]
	v_add_u32_e32 v3, 0x1000, v4
	ds_write2_b64 v3, v[16:17], v[18:19] offset0:4 offset1:133
	v_cndmask_b32_e32 v3, 0, v38, vcc
	v_add_u32_e32 v16, 0x162c, v4
	v_cndmask_b32_e64 v17, 0, v39, s[42:43]
	ds_write2_b32 v16, v3, v17 offset1:1
	v_cndmask_b32_e32 v3, 0, v42, vcc
	v_add_u32_e32 v18, 0x1a34, v4
	v_cndmask_b32_e64 v19, 0, v43, s[42:43]
	v_cndmask_b32_e32 v16, 0, v40, vcc
	v_cndmask_b32_e64 v17, 0, v41, s[42:43]
	ds_write2_b32 v18, v3, v19 offset1:1
	v_cndmask_b32_e32 v18, 0, v44, vcc
	v_cndmask_b32_e64 v19, 0, v45, s[42:43]
	v_add_u32_e32 v3, 0x1800, v4
	ds_write2_b64 v3, v[16:17], v[18:19] offset0:6 offset1:135
	v_cndmask_b32_e32 v3, 0, v46, vcc
	v_add_u32_e32 v16, 0x1e3c, v4
	v_cndmask_b32_e64 v17, 0, v47, s[42:43]
	ds_write2_b32 v16, v3, v17 offset1:1
	v_cndmask_b32_e32 v3, 0, v50, vcc
	v_add_u32_e32 v18, 0x2244, v4
	v_cndmask_b32_e64 v19, 0, v51, s[42:43]
	v_cndmask_b32_e32 v16, 0, v48, vcc
	v_cndmask_b32_e64 v17, 0, v49, s[42:43]
	ds_write2_b32 v18, v3, v19 offset1:1
	v_cndmask_b32_e32 v18, 0, v52, vcc
	v_cndmask_b32_e64 v19, 0, v53, s[42:43]
	v_add_u32_e32 v3, 0x2000, v4
	ds_write2_b64 v3, v[16:17], v[18:19] offset0:8 offset1:137
	v_cndmask_b32_e32 v3, 0, v54, vcc
	v_add_u32_e32 v16, 0x264c, v4
	v_cndmask_b32_e64 v17, 0, v55, s[42:43]
	ds_write2_b32 v16, v3, v17 offset1:1
	v_cndmask_b32_e32 v3, 0, v58, vcc
	v_add_u32_e32 v18, 0x2a54, v4
	v_cndmask_b32_e64 v19, 0, v59, s[42:43]
	v_cndmask_b32_e32 v16, 0, v56, vcc
	v_cndmask_b32_e64 v17, 0, v57, s[42:43]
	ds_write2_b32 v18, v3, v19 offset1:1
	v_cndmask_b32_e32 v18, 0, v60, vcc
	v_cndmask_b32_e64 v19, 0, v61, s[42:43]
	v_add_u32_e32 v3, 0x2800, v4
	ds_write2_b64 v3, v[16:17], v[18:19] offset0:10 offset1:139
	v_cndmask_b32_e32 v3, 0, v62, vcc
	v_add_u32_e32 v16, 0x2e5c, v4
	v_cndmask_b32_e64 v17, 0, v63, s[42:43]
	ds_write2_b32 v16, v3, v17 offset1:1
	v_cndmask_b32_e32 v3, 0, v66, vcc
	v_add_u32_e32 v18, 0x3264, v4
	v_cndmask_b32_e64 v19, 0, v67, s[42:43]
	v_cndmask_b32_e32 v16, 0, v64, vcc
	v_cndmask_b32_e64 v17, 0, v65, s[42:43]
	ds_write2_b32 v18, v3, v19 offset1:1
	v_cndmask_b32_e32 v18, 0, v68, vcc
	v_cndmask_b32_e64 v19, 0, v69, s[42:43]
	v_add_u32_e32 v3, 0x3000, v4
	ds_write2_b64 v3, v[16:17], v[18:19] offset0:12 offset1:141
	v_cndmask_b32_e32 v3, 0, v70, vcc
	v_add_u32_e32 v16, 0x366c, v4
	v_cndmask_b32_e64 v17, 0, v71, s[42:43]
	ds_write2_b32 v16, v3, v17 offset1:1
	v_cndmask_b32_e32 v3, 0, v74, vcc
	v_add_u32_e32 v18, 0x3a74, v4
	v_cndmask_b32_e64 v19, 0, v75, s[42:43]
	v_cndmask_b32_e32 v16, 0, v72, vcc
	v_cndmask_b32_e64 v17, 0, v73, s[42:43]
	ds_write2_b32 v18, v3, v19 offset1:1
	v_cndmask_b32_e32 v18, 0, v76, vcc
	v_cndmask_b32_e64 v19, 0, v77, s[42:43]
	v_add_u32_e32 v3, 0x3800, v4
	ds_write2_b64 v3, v[16:17], v[18:19] offset0:14 offset1:143
	v_cndmask_b32_e32 v3, 0, v14, vcc
	v_add_u32_e32 v14, 0x3e7c, v4
	v_cndmask_b32_e64 v15, 0, v15, s[42:43]
	ds_write2_b32 v14, v3, v15 offset1:1
	ds_read_b32 v14, v6
	ds_read_b32 v15, v6 offset:516
	ds_read_b32 v16, v6 offset:1032
	ds_read_b32 v17, v6 offset:1548
	ds_read_b32 v20, v6 offset:2064
	ds_read_b32 v21, v6 offset:2580
	ds_read_b32 v22, v6 offset:3096
	ds_read_b32 v23, v6 offset:3612
	s_lshl_b64 s[42:43], s[64:65], 1
	s_add_u32 s42, s60, s42
	s_addc_u32 s43, s61, s43
	v_mov_b32_e32 v3, v177
	v_lshl_add_u64 v[18:19], s[42:43], 0, v[2:3]
	v_or_b32_e32 v3, s33, v5
	s_ashr_i32 s6, s33, 31
	s_waitcnt lgkmcnt(0)
	v_cvt_pk_bf16_f32 v14, v14, v15
	v_cvt_pk_bf16_f32 v15, v16, v17
	v_cvt_pk_bf16_f32 v16, v20, v21
	v_cvt_pk_bf16_f32 v17, v22, v23
	s_mul_i32 s6, s58, s6
	v_mul_lo_u32 v22, s59, v3
	v_mad_u64_u32 v[20:21], s[42:43], s58, v3, 0
	v_add3_u32 v21, v21, s6, v22
	v_lshl_add_u64 v[20:21], v[20:21], 1, v[18:19]
	flat_store_dwordx4 v[20:21], v[14:17]
	ds_read_b32 v3, v6 offset:64
	ds_read_b32 v14, v6 offset:580
	ds_read_b32 v15, v6 offset:1096
	ds_read_b32 v16, v6 offset:1612
	ds_read_b32 v17, v6 offset:2128
	ds_read_b32 v20, v6 offset:2644
	ds_read_b32 v21, v6 offset:3160
	ds_read_b32 v22, v6 offset:3676
	s_waitcnt lgkmcnt(0)
	v_cvt_pk_bf16_f32 v14, v3, v14
	v_or_b32_e32 v3, s33, v7
	v_cvt_pk_bf16_f32 v15, v15, v16
	v_cvt_pk_bf16_f32 v16, v17, v20
	v_cvt_pk_bf16_f32 v17, v21, v22
	v_mul_lo_u32 v22, s59, v3
	v_mad_u64_u32 v[20:21], s[42:43], s58, v3, 0
	v_add3_u32 v21, v21, s6, v22
	v_lshl_add_u64 v[20:21], v[20:21], 1, v[18:19]
	flat_store_dwordx4 v[20:21], v[14:17]
	ds_read_b32 v3, v6 offset:128
	ds_read_b32 v14, v6 offset:644
	ds_read_b32 v15, v6 offset:1160
	ds_read_b32 v16, v6 offset:1676
	ds_read_b32 v17, v6 offset:2192
	ds_read_b32 v20, v6 offset:2708
	ds_read_b32 v21, v6 offset:3224
	ds_read_b32 v22, v6 offset:3740
	s_waitcnt lgkmcnt(0)
	v_cvt_pk_bf16_f32 v14, v3, v14
	v_or_b32_e32 v3, s33, v8
	v_cvt_pk_bf16_f32 v15, v15, v16
	v_cvt_pk_bf16_f32 v16, v17, v20
	v_cvt_pk_bf16_f32 v17, v21, v22
	v_mul_lo_u32 v22, s59, v3
	v_mad_u64_u32 v[20:21], s[42:43], s58, v3, 0
	v_add3_u32 v21, v21, s6, v22
	v_lshl_add_u64 v[20:21], v[20:21], 1, v[18:19]
	flat_store_dwordx4 v[20:21], v[14:17]
	ds_read_b32 v3, v6 offset:192
	ds_read_b32 v14, v6 offset:708
	ds_read_b32 v15, v6 offset:1224
	ds_read_b32 v16, v6 offset:1740
	ds_read_b32 v17, v6 offset:2256
	ds_read_b32 v20, v6 offset:2772
	ds_read_b32 v21, v6 offset:3288
	ds_read_b32 v22, v6 offset:3804
	s_waitcnt lgkmcnt(0)
	v_cvt_pk_bf16_f32 v14, v3, v14
	v_or_b32_e32 v3, s33, v9
	v_cvt_pk_bf16_f32 v15, v15, v16
	v_cvt_pk_bf16_f32 v16, v17, v20
	v_cvt_pk_bf16_f32 v17, v21, v22
	v_mul_lo_u32 v22, s59, v3
	v_mad_u64_u32 v[20:21], s[42:43], s58, v3, 0
	v_add3_u32 v21, v21, s6, v22
	v_lshl_add_u64 v[20:21], v[20:21], 1, v[18:19]
	flat_store_dwordx4 v[20:21], v[14:17]
	ds_read_b32 v3, v6 offset:256
	ds_read_b32 v14, v6 offset:772
	ds_read_b32 v15, v6 offset:1288
	ds_read_b32 v16, v6 offset:1804
	ds_read_b32 v17, v6 offset:2320
	ds_read_b32 v20, v6 offset:2836
	ds_read_b32 v21, v6 offset:3352
	ds_read_b32 v22, v6 offset:3868
	s_waitcnt lgkmcnt(0)
	v_cvt_pk_bf16_f32 v14, v3, v14
	v_or_b32_e32 v3, s33, v10
	v_cvt_pk_bf16_f32 v15, v15, v16
	v_cvt_pk_bf16_f32 v16, v17, v20
	v_cvt_pk_bf16_f32 v17, v21, v22
	v_mul_lo_u32 v22, s59, v3
	v_mad_u64_u32 v[20:21], s[42:43], s58, v3, 0
	v_add3_u32 v21, v21, s6, v22
	v_lshl_add_u64 v[20:21], v[20:21], 1, v[18:19]
	flat_store_dwordx4 v[20:21], v[14:17]
	ds_read_b32 v3, v6 offset:320
	ds_read_b32 v14, v6 offset:836
	ds_read_b32 v15, v6 offset:1352
	ds_read_b32 v16, v6 offset:1868
	ds_read_b32 v17, v6 offset:2384
	ds_read_b32 v20, v6 offset:2900
	ds_read_b32 v21, v6 offset:3416
	ds_read_b32 v22, v6 offset:3932
	s_waitcnt lgkmcnt(0)
	v_cvt_pk_bf16_f32 v14, v3, v14
	v_or_b32_e32 v3, s33, v11
	v_cvt_pk_bf16_f32 v15, v15, v16
	v_cvt_pk_bf16_f32 v16, v17, v20
	v_cvt_pk_bf16_f32 v17, v21, v22
	v_mul_lo_u32 v22, s59, v3
	v_mad_u64_u32 v[20:21], s[42:43], s58, v3, 0
	v_add3_u32 v21, v21, s6, v22
	v_lshl_add_u64 v[20:21], v[20:21], 1, v[18:19]
	flat_store_dwordx4 v[20:21], v[14:17]
	ds_read_b32 v3, v6 offset:384
	ds_read_b32 v14, v6 offset:900
	ds_read_b32 v15, v6 offset:1416
	ds_read_b32 v16, v6 offset:1932
	ds_read_b32 v17, v6 offset:2448
	ds_read_b32 v20, v6 offset:2964
	ds_read_b32 v21, v6 offset:3480
	ds_read_b32 v22, v6 offset:3996
	s_waitcnt lgkmcnt(0)
	v_cvt_pk_bf16_f32 v14, v3, v14
	v_or_b32_e32 v3, s33, v12
	v_cvt_pk_bf16_f32 v15, v15, v16
	v_cvt_pk_bf16_f32 v16, v17, v20
	v_cvt_pk_bf16_f32 v17, v21, v22
	v_mul_lo_u32 v22, s59, v3
	v_mad_u64_u32 v[20:21], s[42:43], s58, v3, 0
	v_add3_u32 v21, v21, s6, v22
	v_lshl_add_u64 v[20:21], v[20:21], 1, v[18:19]
	flat_store_dwordx4 v[20:21], v[14:17]
	ds_read_b32 v3, v6 offset:448
	ds_read_b32 v14, v6 offset:964
	ds_read_b32 v15, v6 offset:1480
	ds_read_b32 v16, v6 offset:1996
	ds_read_b32 v17, v6 offset:2512
	ds_read_b32 v20, v6 offset:3028
	ds_read_b32 v21, v6 offset:3544
	ds_read_b32 v22, v6 offset:4060
	s_waitcnt lgkmcnt(0)
	v_cvt_pk_bf16_f32 v14, v3, v14
	v_or_b32_e32 v3, s33, v13
	v_cvt_pk_bf16_f32 v15, v15, v16
	v_cvt_pk_bf16_f32 v16, v17, v20
	v_cvt_pk_bf16_f32 v17, v21, v22
	v_mul_lo_u32 v22, s59, v3
	v_mad_u64_u32 v[20:21], s[42:43], s58, v3, 0
	s_add_i32 s41, s41, s36
	v_add3_u32 v21, v21, s6, v22
	s_add_i32 s6, s41, 0xffffea00
	v_lshl_add_u64 v[18:19], v[20:21], 1, v[18:19]
	s_cmpk_gt_i32 s6, 0xaff
	flat_store_dwordx4 v[18:19], v[14:17]
	s_cbranch_scc1 .LBB0_537

.LBB0_537:
	s_and_b64 vcc, exec, s[86:87]
	s_cbranch_vccz .LBB0_697
	s_cmp_eq_u32 s70, 3
	s_cbranch_scc0 .LBB0_697
	v_readlane_b32 s8, v251, 22
	v_readlane_b32 s9, v251, 23
	s_andn2_b64 vcc, exec, s[8:9]
	s_cbranch_vccnz .LBB0_697
	s_mul_i32 s6, s22, 0x4100
	s_add_i32 s38, s6, 0
	s_add_i32 s39, s88, 0xffffff80
	s_cmpk_gt_i32 s39, 0xaff
	s_cbranch_scc1 .LBB0_620
	v_readlane_b32 s8, v248, 0
	s_ashr_i32 s45, s8, 31
	v_readlane_b32 s9, v248, 1
	s_mov_b32 s44, s8
	s_mul_hi_i32 s41, s8, 0x2c00000
	s_mul_i32 s76, s8, 0x2c00000
	s_add_u32 s8, s90, 0x1eca4000
	s_addc_u32 s9, s91, 0
	s_add_u32 s10, s90, 0x6600000
	s_addc_u32 s11, s91, 0
	s_lshl_b64 s[42:43], s[44:45], 22
	s_add_u32 s12, s90, 0x2280000
	s_addc_u32 s13, s91, 0
	s_lshl_b64 s[46:47], s[44:45], 23
	s_add_u32 s14, s90, 0x1e80000
	s_addc_u32 s15, s91, 0
	s_add_u32 s16, s90, 0x1c80000
	s_addc_u32 s17, s91, 0
	s_lshl_b64 s[50:51], s[44:45], 24
	s_add_u32 s18, s90, 0x1480000
	s_mov_b32 s20, s44
	s_addc_u32 s19, s91, 0
	v_writelane_b32 v248, s20, 0
	s_mul_hi_i32 s6, s44, 0x2630000
	s_mul_i32 s33, s44, 0x2630000
	v_writelane_b32 v248, s21, 1
	s_add_u32 s20, s90, 0xf80000
	s_addc_u32 s21, s91, 0
	v_readlane_b32 s44, v249, 23
	v_readlane_b32 s45, v249, 24
	s_add_u32 s86, s44, s76
	s_addc_u32 s87, s45, s41
	v_readlane_b32 s44, v249, 19
	v_readlane_b32 s45, v249, 20
	s_add_u32 s44, s44, s42
	v_readlane_b32 s52, v249, 29
	s_addc_u32 s45, s45, s43
	v_readlane_b32 s54, v249, 31
	v_readlane_b32 s55, v249, 32
	s_add_u32 s46, s54, s46
	s_addc_u32 s47, s55, s47
	v_readlane_b32 s53, v249, 30
	s_add_u32 s48, s52, s42
	v_readlane_b32 s56, v250, 41
	s_addc_u32 s49, s53, s43
	v_readlane_b32 s62, v250, 47
	v_readlane_b32 s57, v250, 42
	v_readlane_b32 s58, v250, 43
	v_readlane_b32 s59, v250, 44
	v_readlane_b32 s60, v250, 45
	v_readlane_b32 s61, v250, 46
	v_readlane_b32 s63, v250, 48
	s_add_u32 s50, s62, s50
	s_addc_u32 s51, s63, s51
	v_readlane_b32 s52, v250, 51
	v_lshlrev_b32_e32 v2, 3, v128
	v_readlane_b32 s54, v250, 53
	v_readlane_b32 s60, v250, 59
	v_add_u32_e32 v4, s38, v2
	v_and_b32_e32 v2, 24, v2
	v_readlane_b32 s55, v250, 54
	v_readlane_b32 s61, v250, 60
	s_add_u32 s54, s60, s33
	v_lshlrev_b32_e32 v0, 1, v128
	v_lshrrev_b32_e32 v5, 2, v128
	v_mul_u32_u24_e32 v3, 0x204, v2
	v_and_b32_e32 v6, 60, v128
	v_readlane_b32 s67, v249, 2
	s_addc_u32 s55, s61, s6
	v_readlane_b32 s6, v249, 13
	v_or_b32_e32 v1, 1, v0
	v_add3_u32 v6, s38, v3, v6
	v_or_b32_e32 v7, 16, v5
	v_or_b32_e32 v8, 32, v5
	v_or_b32_e32 v9, 48, v5
	v_or_b32_e32 v10, 64, v5
	v_or_b32_e32 v11, 0x50, v5
	v_or_b32_e32 v12, 0x60, v5
	v_or_b32_e32 v13, 0x70, v5
	s_add_i32 s67, s6, s22
	v_lshlrev_b32_e32 v2, 1, v2
	v_readlane_b32 s53, v250, 52
	v_readlane_b32 s56, v250, 55
	v_readlane_b32 s57, v250, 56
	v_readlane_b32 s58, v250, 57
	v_readlane_b32 s59, v250, 58
	v_readlane_b32 s62, v250, 61
	v_readlane_b32 s63, v250, 62
	v_readlane_b32 s64, v250, 63
	v_readlane_b32 s65, v249, 0
	v_readlane_b32 s66, v249, 1
	s_waitcnt vmcnt(0)
	s_branch .LBB0_544

.LBB0_543:
	s_lshl_b32 s62, s71, 5
	s_ashr_i32 s63, s62, 31
	s_lshl_b32 s33, s43, 6
	s_mul_i32 s43, s6, s63
	s_mul_hi_u32 s71, s6, s62
	s_add_i32 s73, s71, s43
	s_mul_i32 s72, s6, s62
	s_lshl_b64 s[72:73], s[72:73], 2
	s_add_u32 s60, s60, s72
	s_addc_u32 s61, s61, s73
	s_ashr_i32 s43, s42, 31
	s_lshl_b64 s[42:43], s[42:43], 2
	s_add_u32 s42, s60, s42
	s_addc_u32 s43, s61, s43
	v_lshlrev_b32_e32 v176, 2, v0
	v_lshl_add_u64 v[14:15], s[42:43], 0, v[176:177]
	global_load_dwordx2 v[16:17], v176, s[42:43] nt
	s_lshl_b32 s42, s6, 1
	s_mov_b32 s43, s7
	v_lshl_add_u64 v[20:21], s[42:43], 2, v[14:15]
	s_mul_i32 s42, s6, 3
	v_lshl_add_u64 v[22:23], s[42:43], 2, v[14:15]
	s_lshl_b32 s42, s6, 2
	v_lshl_add_u64 v[24:25], s[42:43], 2, v[14:15]
	s_mul_i32 s42, s6, 5
	v_lshl_add_u64 v[26:27], s[42:43], 2, v[14:15]
	s_mul_i32 s42, s6, 6
	v_lshl_add_u64 v[28:29], s[42:43], 2, v[14:15]
	s_mul_i32 s42, s6, 7
	v_lshl_add_u64 v[30:31], s[42:43], 2, v[14:15]
	s_lshl_b32 s42, s6, 3
	v_lshl_add_u64 v[32:33], s[42:43], 2, v[14:15]
	s_mul_i32 s42, s6, 9
	v_lshl_add_u64 v[34:35], s[42:43], 2, v[14:15]
	s_mul_i32 s42, s6, 10
	v_lshl_add_u64 v[18:19], s[6:7], 2, v[14:15]
	v_lshl_add_u64 v[36:37], s[42:43], 2, v[14:15]
	s_mul_i32 s42, s6, 11
	global_load_dwordx2 v[18:19], v[18:19], off nt
	s_nop 0
	global_load_dwordx2 v[20:21], v[20:21], off nt
	s_nop 0
	global_load_dwordx2 v[22:23], v[22:23], off nt
	s_nop 0
	global_load_dwordx2 v[24:25], v[24:25], off nt
	v_lshl_add_u64 v[38:39], s[42:43], 2, v[14:15]
	s_mul_i32 s42, s6, 12
	v_lshl_add_u64 v[40:41], s[42:43], 2, v[14:15]
	s_mul_i32 s42, s6, 13
	v_lshl_add_u64 v[42:43], s[42:43], 2, v[14:15]
	s_mul_i32 s42, s6, 14
	global_load_dwordx2 v[26:27], v[26:27], off nt
	s_nop 0
	global_load_dwordx2 v[28:29], v[28:29], off nt
	s_nop 0
	global_load_dwordx2 v[30:31], v[30:31], off nt
	s_nop 0
	global_load_dwordx2 v[32:33], v[32:33], off nt
	v_lshl_add_u64 v[44:45], s[42:43], 2, v[14:15]
	s_mul_i32 s42, s6, 15
	v_lshl_add_u64 v[46:47], s[42:43], 2, v[14:15]
	s_lshl_b32 s42, s6, 4
	v_lshl_add_u64 v[48:49], s[42:43], 2, v[14:15]
	s_mul_i32 s42, s6, 17
	global_load_dwordx2 v[34:35], v[34:35], off nt
	s_nop 0
	global_load_dwordx2 v[36:37], v[36:37], off nt
	s_nop 0
	global_load_dwordx2 v[38:39], v[38:39], off nt
	s_nop 0
	global_load_dwordx2 v[40:41], v[40:41], off nt
	v_lshl_add_u64 v[50:51], s[42:43], 2, v[14:15]
	s_mul_i32 s42, s6, 18
	v_lshl_add_u64 v[52:53], s[42:43], 2, v[14:15]
	s_mul_i32 s42, s6, 19
	v_lshl_add_u64 v[54:55], s[42:43], 2, v[14:15]
	s_mul_i32 s42, s6, 20
	global_load_dwordx2 v[42:43], v[42:43], off nt
	s_nop 0
	global_load_dwordx2 v[44:45], v[44:45], off nt
	s_nop 0
	global_load_dwordx2 v[46:47], v[46:47], off nt
	s_nop 0
	global_load_dwordx2 v[48:49], v[48:49], off nt
	v_lshl_add_u64 v[56:57], s[42:43], 2, v[14:15]
	s_mul_i32 s42, s6, 21
	v_lshl_add_u64 v[58:59], s[42:43], 2, v[14:15]
	s_mul_i32 s42, s6, 22
	v_lshl_add_u64 v[60:61], s[42:43], 2, v[14:15]
	s_mul_i32 s42, s6, 23
	global_load_dwordx2 v[50:51], v[50:51], off nt
	s_nop 0
	global_load_dwordx2 v[52:53], v[52:53], off nt
	s_nop 0
	global_load_dwordx2 v[54:55], v[54:55], off nt
	s_nop 0
	global_load_dwordx2 v[56:57], v[56:57], off nt
	v_lshl_add_u64 v[62:63], s[42:43], 2, v[14:15]
	s_mul_i32 s42, s6, 24
	s_waitcnt lgkmcnt(0)
	v_lshl_add_u64 v[64:65], s[42:43], 2, v[14:15]
	s_mul_i32 s42, s6, 25
	v_lshl_add_u64 v[66:67], s[42:43], 2, v[14:15]
	s_mul_i32 s42, s6, 26
	global_load_dwordx2 v[58:59], v[58:59], off nt
	s_nop 0
	global_load_dwordx2 v[60:61], v[60:61], off nt
	s_nop 0
	global_load_dwordx2 v[62:63], v[62:63], off nt
	s_nop 0
	global_load_dwordx2 v[64:65], v[64:65], off nt
	v_lshl_add_u64 v[68:69], s[42:43], 2, v[14:15]
	s_mul_i32 s42, s6, 27
	v_lshl_add_u64 v[70:71], s[42:43], 2, v[14:15]
	s_mul_i32 s42, s6, 28
	v_lshl_add_u64 v[72:73], s[42:43], 2, v[14:15]
	s_mul_i32 s42, s6, 29
	global_load_dwordx2 v[66:67], v[66:67], off nt
	s_nop 0
	global_load_dwordx2 v[68:69], v[68:69], off nt
	s_nop 0
	global_load_dwordx2 v[70:71], v[70:71], off nt
	s_nop 0
	global_load_dwordx2 v[72:73], v[72:73], off nt
	v_lshl_add_u64 v[74:75], s[42:43], 2, v[14:15]
	s_mul_i32 s42, s6, 30
	s_mul_i32 s6, s6, 31
	v_lshl_add_u64 v[76:77], s[42:43], 2, v[14:15]
	v_lshl_add_u64 v[14:15], s[6:7], 2, v[14:15]
	global_load_dwordx2 v[74:75], v[74:75], off nt
	s_nop 0
	global_load_dwordx2 v[76:77], v[76:77], off nt
	s_nop 0
	global_load_dwordx2 v[14:15], v[14:15], off nt
	v_cmp_gt_u32_e32 vcc, s69, v0
	v_cmp_gt_u32_e64 s[42:43], s69, v1
	s_waitcnt vmcnt(0)
	v_cndmask_b32_e32 v16, 0, v16, vcc
	v_cndmask_b32_e64 v17, 0, v17, s[42:43]
	v_cndmask_b32_e32 v3, 0, v18, vcc
	v_cndmask_b32_e64 v18, 0, v19, s[42:43]
	ds_write2_b32 v4, v3, v18 offset0:129 offset1:130
	v_cndmask_b32_e32 v18, 0, v20, vcc
	v_cndmask_b32_e64 v19, 0, v21, s[42:43]
	ds_write2_b64 v4, v[16:17], v[18:19] offset1:129
	v_cndmask_b32_e32 v3, 0, v22, vcc
	v_add_u32_e32 v16, 0x60c, v4
	v_cndmask_b32_e64 v17, 0, v23, s[42:43]
	ds_write2_b32 v16, v3, v17 offset1:1
	v_cndmask_b32_e32 v3, 0, v26, vcc
	v_add_u32_e32 v18, 0xa14, v4
	v_cndmask_b32_e64 v19, 0, v27, s[42:43]
	v_cndmask_b32_e32 v16, 0, v24, vcc
	v_cndmask_b32_e64 v17, 0, v25, s[42:43]
	ds_write2_b32 v18, v3, v19 offset1:1
	v_cndmask_b32_e32 v18, 0, v28, vcc
	v_cndmask_b32_e64 v19, 0, v29, s[42:43]
	v_add_u32_e32 v3, 0x800, v4
	ds_write2_b64 v3, v[16:17], v[18:19] offset0:2 offset1:131
	v_cndmask_b32_e32 v3, 0, v30, vcc
	v_add_u32_e32 v16, 0xe1c, v4
	v_cndmask_b32_e64 v17, 0, v31, s[42:43]
	ds_write2_b32 v16, v3, v17 offset1:1
	v_cndmask_b32_e32 v3, 0, v34, vcc
	v_add_u32_e32 v18, 0x1224, v4
	v_cndmask_b32_e64 v19, 0, v35, s[42:43]
	v_cndmask_b32_e32 v16, 0, v32, vcc
	v_cndmask_b32_e64 v17, 0, v33, s[42:43]
	ds_write2_b32 v18, v3, v19 offset1:1
	v_cndmask_b32_e32 v18, 0, v36, vcc
	v_cndmask_b32_e64 v19, 0, v37, s[42:43]
	v_add_u32_e32 v3, 0x1000, v4
	ds_write2_b64 v3, v[16:17], v[18:19] offset0:4 offset1:133
	v_cndmask_b32_e32 v3, 0, v38, vcc
	v_add_u32_e32 v16, 0x162c, v4
	v_cndmask_b32_e64 v17, 0, v39, s[42:43]
	ds_write2_b32 v16, v3, v17 offset1:1
	v_cndmask_b32_e32 v3, 0, v42, vcc
	v_add_u32_e32 v18, 0x1a34, v4
	v_cndmask_b32_e64 v19, 0, v43, s[42:43]
	v_cndmask_b32_e32 v16, 0, v40, vcc
	v_cndmask_b32_e64 v17, 0, v41, s[42:43]
	ds_write2_b32 v18, v3, v19 offset1:1
	v_cndmask_b32_e32 v18, 0, v44, vcc
	v_cndmask_b32_e64 v19, 0, v45, s[42:43]
	v_add_u32_e32 v3, 0x1800, v4
	ds_write2_b64 v3, v[16:17], v[18:19] offset0:6 offset1:135
	v_cndmask_b32_e32 v3, 0, v46, vcc
	v_add_u32_e32 v16, 0x1e3c, v4
	v_cndmask_b32_e64 v17, 0, v47, s[42:43]
	ds_write2_b32 v16, v3, v17 offset1:1
	v_cndmask_b32_e32 v3, 0, v50, vcc
	v_add_u32_e32 v18, 0x2244, v4
	v_cndmask_b32_e64 v19, 0, v51, s[42:43]
	v_cndmask_b32_e32 v16, 0, v48, vcc
	v_cndmask_b32_e64 v17, 0, v49, s[42:43]
	ds_write2_b32 v18, v3, v19 offset1:1
	v_cndmask_b32_e32 v18, 0, v52, vcc
	v_cndmask_b32_e64 v19, 0, v53, s[42:43]
	v_add_u32_e32 v3, 0x2000, v4
	ds_write2_b64 v3, v[16:17], v[18:19] offset0:8 offset1:137
	v_cndmask_b32_e32 v3, 0, v54, vcc
	v_add_u32_e32 v16, 0x264c, v4
	v_cndmask_b32_e64 v17, 0, v55, s[42:43]
	ds_write2_b32 v16, v3, v17 offset1:1
	v_cndmask_b32_e32 v3, 0, v58, vcc
	v_add_u32_e32 v18, 0x2a54, v4
	v_cndmask_b32_e64 v19, 0, v59, s[42:43]
	v_cndmask_b32_e32 v16, 0, v56, vcc
	v_cndmask_b32_e64 v17, 0, v57, s[42:43]
	ds_write2_b32 v18, v3, v19 offset1:1
	v_cndmask_b32_e32 v18, 0, v60, vcc
	v_cndmask_b32_e64 v19, 0, v61, s[42:43]
	v_add_u32_e32 v3, 0x2800, v4
	ds_write2_b64 v3, v[16:17], v[18:19] offset0:10 offset1:139
	v_cndmask_b32_e32 v3, 0, v62, vcc
	v_add_u32_e32 v16, 0x2e5c, v4
	v_cndmask_b32_e64 v17, 0, v63, s[42:43]
	ds_write2_b32 v16, v3, v17 offset1:1
	v_cndmask_b32_e32 v3, 0, v66, vcc
	v_add_u32_e32 v18, 0x3264, v4
	v_cndmask_b32_e64 v19, 0, v67, s[42:43]
	v_cndmask_b32_e32 v16, 0, v64, vcc
	v_cndmask_b32_e64 v17, 0, v65, s[42:43]
	ds_write2_b32 v18, v3, v19 offset1:1
	v_cndmask_b32_e32 v18, 0, v68, vcc
	v_cndmask_b32_e64 v19, 0, v69, s[42:43]
	v_add_u32_e32 v3, 0x3000, v4
	ds_write2_b64 v3, v[16:17], v[18:19] offset0:12 offset1:141
	v_cndmask_b32_e32 v3, 0, v70, vcc
	v_add_u32_e32 v16, 0x366c, v4
	v_cndmask_b32_e64 v17, 0, v71, s[42:43]
	ds_write2_b32 v16, v3, v17 offset1:1
	v_cndmask_b32_e32 v3, 0, v74, vcc
	v_add_u32_e32 v18, 0x3a74, v4
	v_cndmask_b32_e64 v19, 0, v75, s[42:43]
	v_cndmask_b32_e32 v16, 0, v72, vcc
	v_cndmask_b32_e64 v17, 0, v73, s[42:43]
	ds_write2_b32 v18, v3, v19 offset1:1
	v_cndmask_b32_e32 v18, 0, v76, vcc
	v_cndmask_b32_e64 v19, 0, v77, s[42:43]
	v_add_u32_e32 v3, 0x3800, v4
	ds_write2_b64 v3, v[16:17], v[18:19] offset0:14 offset1:143
	v_cndmask_b32_e32 v3, 0, v14, vcc
	v_add_u32_e32 v14, 0x3e7c, v4
	v_cndmask_b32_e64 v15, 0, v15, s[42:43]
	ds_write2_b32 v14, v3, v15 offset1:1
	ds_read_b32 v14, v6
	ds_read_b32 v15, v6 offset:516
	ds_read_b32 v16, v6 offset:1032
	ds_read_b32 v17, v6 offset:1548
	ds_read_b32 v20, v6 offset:2064
	ds_read_b32 v21, v6 offset:2580
	ds_read_b32 v22, v6 offset:3096
	ds_read_b32 v23, v6 offset:3612
	s_lshl_b64 s[42:43], s[62:63], 1
	s_add_u32 s42, s58, s42
	s_addc_u32 s43, s59, s43
	v_mov_b32_e32 v3, v177
	v_lshl_add_u64 v[18:19], s[42:43], 0, v[2:3]
	v_or_b32_e32 v3, s33, v5
	s_ashr_i32 s6, s33, 31
	s_waitcnt lgkmcnt(0)
	v_cvt_pk_bf16_f32 v14, v14, v15
	v_cvt_pk_bf16_f32 v15, v16, v17
	v_cvt_pk_bf16_f32 v16, v20, v21
	v_cvt_pk_bf16_f32 v17, v22, v23
	s_mul_i32 s6, s56, s6
	v_mul_lo_u32 v22, s57, v3
	v_mad_u64_u32 v[20:21], s[42:43], s56, v3, 0
	v_add3_u32 v21, v21, s6, v22
	v_lshl_add_u64 v[20:21], v[20:21], 1, v[18:19]
	flat_store_dwordx4 v[20:21], v[14:17]
	ds_read_b32 v3, v6 offset:64
	ds_read_b32 v14, v6 offset:580
	ds_read_b32 v15, v6 offset:1096
	ds_read_b32 v16, v6 offset:1612
	ds_read_b32 v17, v6 offset:2128
	ds_read_b32 v20, v6 offset:2644
	ds_read_b32 v21, v6 offset:3160
	ds_read_b32 v22, v6 offset:3676
	s_waitcnt lgkmcnt(0)
	v_cvt_pk_bf16_f32 v14, v3, v14
	v_or_b32_e32 v3, s33, v7
	v_cvt_pk_bf16_f32 v15, v15, v16
	v_cvt_pk_bf16_f32 v16, v17, v20
	v_cvt_pk_bf16_f32 v17, v21, v22
	v_mul_lo_u32 v22, s57, v3
	v_mad_u64_u32 v[20:21], s[42:43], s56, v3, 0
	v_add3_u32 v21, v21, s6, v22
	v_lshl_add_u64 v[20:21], v[20:21], 1, v[18:19]
	flat_store_dwordx4 v[20:21], v[14:17]
	ds_read_b32 v3, v6 offset:128
	ds_read_b32 v14, v6 offset:644
	ds_read_b32 v15, v6 offset:1160
	ds_read_b32 v16, v6 offset:1676
	ds_read_b32 v17, v6 offset:2192
	ds_read_b32 v20, v6 offset:2708
	ds_read_b32 v21, v6 offset:3224
	ds_read_b32 v22, v6 offset:3740
	s_waitcnt lgkmcnt(0)
	v_cvt_pk_bf16_f32 v14, v3, v14
	v_or_b32_e32 v3, s33, v8
	v_cvt_pk_bf16_f32 v15, v15, v16
	v_cvt_pk_bf16_f32 v16, v17, v20
	v_cvt_pk_bf16_f32 v17, v21, v22
	v_mul_lo_u32 v22, s57, v3
	v_mad_u64_u32 v[20:21], s[42:43], s56, v3, 0
	v_add3_u32 v21, v21, s6, v22
	v_lshl_add_u64 v[20:21], v[20:21], 1, v[18:19]
	flat_store_dwordx4 v[20:21], v[14:17]
	ds_read_b32 v3, v6 offset:192
	ds_read_b32 v14, v6 offset:708
	ds_read_b32 v15, v6 offset:1224
	ds_read_b32 v16, v6 offset:1740
	ds_read_b32 v17, v6 offset:2256
	ds_read_b32 v20, v6 offset:2772
	ds_read_b32 v21, v6 offset:3288
	ds_read_b32 v22, v6 offset:3804
	s_waitcnt lgkmcnt(0)
	v_cvt_pk_bf16_f32 v14, v3, v14
	v_or_b32_e32 v3, s33, v9
	v_cvt_pk_bf16_f32 v15, v15, v16
	v_cvt_pk_bf16_f32 v16, v17, v20
	v_cvt_pk_bf16_f32 v17, v21, v22
	v_mul_lo_u32 v22, s57, v3
	v_mad_u64_u32 v[20:21], s[42:43], s56, v3, 0
	v_add3_u32 v21, v21, s6, v22
	v_lshl_add_u64 v[20:21], v[20:21], 1, v[18:19]
	flat_store_dwordx4 v[20:21], v[14:17]
	ds_read_b32 v3, v6 offset:256
	ds_read_b32 v14, v6 offset:772
	ds_read_b32 v15, v6 offset:1288
	ds_read_b32 v16, v6 offset:1804
	ds_read_b32 v17, v6 offset:2320
	ds_read_b32 v20, v6 offset:2836
	ds_read_b32 v21, v6 offset:3352
	ds_read_b32 v22, v6 offset:3868
	s_waitcnt lgkmcnt(0)
	v_cvt_pk_bf16_f32 v14, v3, v14
	v_or_b32_e32 v3, s33, v10
	v_cvt_pk_bf16_f32 v15, v15, v16
	v_cvt_pk_bf16_f32 v16, v17, v20
	v_cvt_pk_bf16_f32 v17, v21, v22
	v_mul_lo_u32 v22, s57, v3
	v_mad_u64_u32 v[20:21], s[42:43], s56, v3, 0
	v_add3_u32 v21, v21, s6, v22
	v_lshl_add_u64 v[20:21], v[20:21], 1, v[18:19]
	flat_store_dwordx4 v[20:21], v[14:17]
	ds_read_b32 v3, v6 offset:320
	ds_read_b32 v14, v6 offset:836
	ds_read_b32 v15, v6 offset:1352
	ds_read_b32 v16, v6 offset:1868
	ds_read_b32 v17, v6 offset:2384
	ds_read_b32 v20, v6 offset:2900
	ds_read_b32 v21, v6 offset:3416
	ds_read_b32 v22, v6 offset:3932
	s_waitcnt lgkmcnt(0)
	v_cvt_pk_bf16_f32 v14, v3, v14
	v_or_b32_e32 v3, s33, v11
	v_cvt_pk_bf16_f32 v15, v15, v16
	v_cvt_pk_bf16_f32 v16, v17, v20
	v_cvt_pk_bf16_f32 v17, v21, v22
	v_mul_lo_u32 v22, s57, v3
	v_mad_u64_u32 v[20:21], s[42:43], s56, v3, 0
	v_add3_u32 v21, v21, s6, v22
	v_lshl_add_u64 v[20:21], v[20:21], 1, v[18:19]
	flat_store_dwordx4 v[20:21], v[14:17]
	ds_read_b32 v3, v6 offset:384
	ds_read_b32 v14, v6 offset:900
	ds_read_b32 v15, v6 offset:1416
	ds_read_b32 v16, v6 offset:1932
	ds_read_b32 v17, v6 offset:2448
	ds_read_b32 v20, v6 offset:2964
	ds_read_b32 v21, v6 offset:3480
	ds_read_b32 v22, v6 offset:3996
	s_waitcnt lgkmcnt(0)
	v_cvt_pk_bf16_f32 v14, v3, v14
	v_or_b32_e32 v3, s33, v12
	v_cvt_pk_bf16_f32 v15, v15, v16
	v_cvt_pk_bf16_f32 v16, v17, v20
	v_cvt_pk_bf16_f32 v17, v21, v22
	v_mul_lo_u32 v22, s57, v3
	v_mad_u64_u32 v[20:21], s[42:43], s56, v3, 0
	v_add3_u32 v21, v21, s6, v22
	v_lshl_add_u64 v[20:21], v[20:21], 1, v[18:19]
	flat_store_dwordx4 v[20:21], v[14:17]
	ds_read_b32 v3, v6 offset:448
	ds_read_b32 v14, v6 offset:964
	ds_read_b32 v15, v6 offset:1480
	ds_read_b32 v16, v6 offset:1996
	ds_read_b32 v17, v6 offset:2512
	ds_read_b32 v20, v6 offset:3028
	ds_read_b32 v21, v6 offset:3544
	ds_read_b32 v22, v6 offset:4060
	s_waitcnt lgkmcnt(0)
	v_cvt_pk_bf16_f32 v14, v3, v14
	v_or_b32_e32 v3, s33, v13
	v_cvt_pk_bf16_f32 v15, v15, v16
	v_cvt_pk_bf16_f32 v16, v17, v20
	v_cvt_pk_bf16_f32 v17, v21, v22
	v_mul_lo_u32 v22, s57, v3
	v_mad_u64_u32 v[20:21], s[42:43], s56, v3, 0
	v_add3_u32 v21, v21, s6, v22
	s_addk_i32 s67, 0x780
	v_lshl_add_u64 v[18:19], v[20:21], 1, v[18:19]
	s_cmpk_lt_i32 s68, 0x380
	flat_store_dwordx4 v[18:19], v[14:17]
	s_cbranch_scc0 .LBB0_620

.LBB0_620:
	s_cmpk_gt_i32 s39, 0x3bf
	s_cbranch_scc1 .LBB0_697
	v_readlane_b32 s8, v248, 0
	s_ashr_i32 s21, s8, 31
	v_readlane_b32 s9, v248, 1
	s_mov_b32 s20, s8
	s_add_u32 s8, s90, 0x6600000
	s_addc_u32 s9, s91, 0
	s_lshl_b64 s[42:43], s[20:21], 22
	s_add_u32 s10, s90, 0x2280000
	s_addc_u32 s11, s91, 0
	s_lshl_b64 s[44:45], s[20:21], 23
	s_add_u32 s12, s90, 0x1e80000
	s_addc_u32 s13, s91, 0
	s_add_u32 s14, s90, 0x1c80000
	s_addc_u32 s15, s91, 0
	s_lshl_b64 s[46:47], s[20:21], 24
	s_add_u32 s16, s90, 0x1480000
	s_mov_b32 s18, s20
	s_addc_u32 s17, s91, 0
	v_writelane_b32 v248, s18, 0
	s_mul_hi_i32 s6, s20, 0x2630000
	s_mul_i32 s33, s20, 0x2630000
	v_writelane_b32 v248, s19, 1
	s_add_u32 s18, s90, 0xf80000
	s_addc_u32 s19, s91, 0
	v_readlane_b32 s20, v249, 19
	v_readlane_b32 s21, v249, 20
	s_add_u32 s20, s20, s42
	v_readlane_b32 s48, v249, 29
	s_addc_u32 s21, s21, s43
	v_readlane_b32 s50, v249, 31
	v_readlane_b32 s51, v249, 32
	s_add_u32 s64, s50, s44
	s_addc_u32 s65, s51, s45
	v_readlane_b32 s49, v249, 30
	s_add_u32 s44, s48, s42
	v_readlane_b32 s56, v250, 41
	s_addc_u32 s45, s49, s43
	v_readlane_b32 s62, v250, 47
	v_readlane_b32 s57, v250, 42
	v_readlane_b32 s58, v250, 43
	v_readlane_b32 s59, v250, 44
	v_readlane_b32 s60, v250, 45
	v_readlane_b32 s61, v250, 46
	v_readlane_b32 s63, v250, 48
	s_add_u32 s46, s62, s46
	s_addc_u32 s47, s63, s47
	v_readlane_b32 s48, v250, 51
	v_lshlrev_b32_e32 v2, 3, v128
	v_readlane_b32 s56, v250, 59
	v_add_u32_e32 v4, s38, v2
	v_and_b32_e32 v2, 24, v2
	v_readlane_b32 s49, v250, 52
	v_readlane_b32 s57, v250, 60
	s_add_u32 s48, s56, s33
	v_lshlrev_b32_e32 v0, 1, v128
	v_lshrrev_b32_e32 v5, 2, v128
	v_mul_u32_u24_e32 v3, 0x204, v2
	v_and_b32_e32 v6, 60, v128
	s_addc_u32 s49, s57, s6
	v_readlane_b32 s6, v249, 14
	v_or_b32_e32 v1, 1, v0
	v_add3_u32 v6, s38, v3, v6
	v_or_b32_e32 v7, 16, v5
	v_or_b32_e32 v8, 32, v5
	v_or_b32_e32 v9, 48, v5
	v_or_b32_e32 v10, 64, v5
	v_or_b32_e32 v11, 0x50, v5
	v_or_b32_e32 v12, 0x60, v5
	v_or_b32_e32 v13, 0x70, v5
	s_add_i32 s38, s6, s22
	v_lshlrev_b32_e32 v2, 1, v2
	v_readlane_b32 s50, v250, 53
	v_readlane_b32 s51, v250, 54
	v_readlane_b32 s52, v250, 55
	v_readlane_b32 s53, v250, 56
	v_readlane_b32 s54, v250, 57
	v_readlane_b32 s55, v250, 58
	v_readlane_b32 s58, v250, 61
	v_readlane_b32 s59, v250, 62
	v_readlane_b32 s60, v250, 63
	v_readlane_b32 s61, v249, 0
	v_readlane_b32 s62, v249, 1
	v_readlane_b32 s63, v249, 2
	s_waitcnt vmcnt(0)
	s_branch .LBB0_624

.LBB0_623:
	s_lshl_b32 s58, s62, 5
	s_ashr_i32 s59, s58, 31
	s_lshl_b32 s33, s43, 6
	s_mul_i32 s43, s6, s59
	s_mul_hi_u32 s62, s6, s58
	s_add_i32 s63, s62, s43
	s_mul_i32 s62, s6, s58
	s_lshl_b64 s[62:63], s[62:63], 2
	s_add_u32 s56, s56, s62
	s_addc_u32 s57, s57, s63
	s_ashr_i32 s43, s42, 31
	s_lshl_b64 s[42:43], s[42:43], 2
	s_add_u32 s42, s56, s42
	s_addc_u32 s43, s57, s43
	v_lshlrev_b32_e32 v176, 2, v0
	v_lshl_add_u64 v[14:15], s[42:43], 0, v[176:177]
	global_load_dwordx2 v[16:17], v176, s[42:43] nt
	s_lshl_b32 s42, s6, 1
	s_mov_b32 s43, s7
	v_lshl_add_u64 v[20:21], s[42:43], 2, v[14:15]
	s_mul_i32 s42, s6, 3
	v_lshl_add_u64 v[22:23], s[42:43], 2, v[14:15]
	s_lshl_b32 s42, s6, 2
	v_lshl_add_u64 v[24:25], s[42:43], 2, v[14:15]
	s_mul_i32 s42, s6, 5
	v_lshl_add_u64 v[26:27], s[42:43], 2, v[14:15]
	s_mul_i32 s42, s6, 6
	v_lshl_add_u64 v[28:29], s[42:43], 2, v[14:15]
	s_mul_i32 s42, s6, 7
	v_lshl_add_u64 v[30:31], s[42:43], 2, v[14:15]
	s_lshl_b32 s42, s6, 3
	v_lshl_add_u64 v[32:33], s[42:43], 2, v[14:15]
	s_mul_i32 s42, s6, 9
	v_lshl_add_u64 v[34:35], s[42:43], 2, v[14:15]
	s_mul_i32 s42, s6, 10
	v_lshl_add_u64 v[18:19], s[6:7], 2, v[14:15]
	v_lshl_add_u64 v[36:37], s[42:43], 2, v[14:15]
	s_mul_i32 s42, s6, 11
	global_load_dwordx2 v[18:19], v[18:19], off nt
	s_nop 0
	global_load_dwordx2 v[20:21], v[20:21], off nt
	s_nop 0
	global_load_dwordx2 v[22:23], v[22:23], off nt
	s_nop 0
	global_load_dwordx2 v[24:25], v[24:25], off nt
	v_lshl_add_u64 v[38:39], s[42:43], 2, v[14:15]
	s_mul_i32 s42, s6, 12
	v_lshl_add_u64 v[40:41], s[42:43], 2, v[14:15]
	s_mul_i32 s42, s6, 13
	v_lshl_add_u64 v[42:43], s[42:43], 2, v[14:15]
	s_mul_i32 s42, s6, 14
	global_load_dwordx2 v[26:27], v[26:27], off nt
	s_nop 0
	global_load_dwordx2 v[28:29], v[28:29], off nt
	s_nop 0
	global_load_dwordx2 v[30:31], v[30:31], off nt
	s_nop 0
	global_load_dwordx2 v[32:33], v[32:33], off nt
	v_lshl_add_u64 v[44:45], s[42:43], 2, v[14:15]
	s_mul_i32 s42, s6, 15
	v_lshl_add_u64 v[46:47], s[42:43], 2, v[14:15]
	s_lshl_b32 s42, s6, 4
	v_lshl_add_u64 v[48:49], s[42:43], 2, v[14:15]
	s_mul_i32 s42, s6, 17
	global_load_dwordx2 v[34:35], v[34:35], off nt
	s_nop 0
	global_load_dwordx2 v[36:37], v[36:37], off nt
	s_nop 0
	global_load_dwordx2 v[38:39], v[38:39], off nt
	s_nop 0
	global_load_dwordx2 v[40:41], v[40:41], off nt
	v_lshl_add_u64 v[50:51], s[42:43], 2, v[14:15]
	s_mul_i32 s42, s6, 18
	v_lshl_add_u64 v[52:53], s[42:43], 2, v[14:15]
	s_mul_i32 s42, s6, 19
	v_lshl_add_u64 v[54:55], s[42:43], 2, v[14:15]
	s_mul_i32 s42, s6, 20
	global_load_dwordx2 v[42:43], v[42:43], off nt
	s_nop 0
	global_load_dwordx2 v[44:45], v[44:45], off nt
	s_nop 0
	global_load_dwordx2 v[46:47], v[46:47], off nt
	s_nop 0
	global_load_dwordx2 v[48:49], v[48:49], off nt
	v_lshl_add_u64 v[56:57], s[42:43], 2, v[14:15]
	s_mul_i32 s42, s6, 21
	v_lshl_add_u64 v[58:59], s[42:43], 2, v[14:15]
	s_mul_i32 s42, s6, 22
	v_lshl_add_u64 v[60:61], s[42:43], 2, v[14:15]
	s_mul_i32 s42, s6, 23
	global_load_dwordx2 v[50:51], v[50:51], off nt
	s_nop 0
	global_load_dwordx2 v[52:53], v[52:53], off nt
	s_nop 0
	global_load_dwordx2 v[54:55], v[54:55], off nt
	s_nop 0
	global_load_dwordx2 v[56:57], v[56:57], off nt
	v_lshl_add_u64 v[62:63], s[42:43], 2, v[14:15]
	s_mul_i32 s42, s6, 24
	s_waitcnt lgkmcnt(0)
	v_lshl_add_u64 v[64:65], s[42:43], 2, v[14:15]
	s_mul_i32 s42, s6, 25
	v_lshl_add_u64 v[66:67], s[42:43], 2, v[14:15]
	s_mul_i32 s42, s6, 26
	global_load_dwordx2 v[58:59], v[58:59], off nt
	s_nop 0
	global_load_dwordx2 v[60:61], v[60:61], off nt
	s_nop 0
	global_load_dwordx2 v[62:63], v[62:63], off nt
	s_nop 0
	global_load_dwordx2 v[64:65], v[64:65], off nt
	v_lshl_add_u64 v[68:69], s[42:43], 2, v[14:15]
	s_mul_i32 s42, s6, 27
	v_lshl_add_u64 v[70:71], s[42:43], 2, v[14:15]
	s_mul_i32 s42, s6, 28
	v_lshl_add_u64 v[72:73], s[42:43], 2, v[14:15]
	s_mul_i32 s42, s6, 29
	global_load_dwordx2 v[66:67], v[66:67], off nt
	s_nop 0
	global_load_dwordx2 v[68:69], v[68:69], off nt
	s_nop 0
	global_load_dwordx2 v[70:71], v[70:71], off nt
	s_nop 0
	global_load_dwordx2 v[72:73], v[72:73], off nt
	v_lshl_add_u64 v[74:75], s[42:43], 2, v[14:15]
	s_mul_i32 s42, s6, 30
	s_mul_i32 s6, s6, 31
	v_lshl_add_u64 v[76:77], s[42:43], 2, v[14:15]
	v_lshl_add_u64 v[14:15], s[6:7], 2, v[14:15]
	global_load_dwordx2 v[74:75], v[74:75], off nt
	s_nop 0
	global_load_dwordx2 v[76:77], v[76:77], off nt
	s_nop 0
	global_load_dwordx2 v[14:15], v[14:15], off nt
	v_cmp_gt_u32_e32 vcc, s41, v0
	v_cmp_gt_u32_e64 s[42:43], s41, v1
	s_waitcnt vmcnt(0)
	v_cndmask_b32_e32 v16, 0, v16, vcc
	v_cndmask_b32_e64 v17, 0, v17, s[42:43]
	v_cndmask_b32_e32 v3, 0, v18, vcc
	v_cndmask_b32_e64 v18, 0, v19, s[42:43]
	ds_write2_b32 v4, v3, v18 offset0:129 offset1:130
	v_cndmask_b32_e32 v18, 0, v20, vcc
	v_cndmask_b32_e64 v19, 0, v21, s[42:43]
	ds_write2_b64 v4, v[16:17], v[18:19] offset1:129
	v_cndmask_b32_e32 v3, 0, v22, vcc
	v_add_u32_e32 v16, 0x60c, v4
	v_cndmask_b32_e64 v17, 0, v23, s[42:43]
	ds_write2_b32 v16, v3, v17 offset1:1
	v_cndmask_b32_e32 v3, 0, v26, vcc
	v_add_u32_e32 v18, 0xa14, v4
	v_cndmask_b32_e64 v19, 0, v27, s[42:43]
	v_cndmask_b32_e32 v16, 0, v24, vcc
	v_cndmask_b32_e64 v17, 0, v25, s[42:43]
	ds_write2_b32 v18, v3, v19 offset1:1
	v_cndmask_b32_e32 v18, 0, v28, vcc
	v_cndmask_b32_e64 v19, 0, v29, s[42:43]
	v_add_u32_e32 v3, 0x800, v4
	ds_write2_b64 v3, v[16:17], v[18:19] offset0:2 offset1:131
	v_cndmask_b32_e32 v3, 0, v30, vcc
	v_add_u32_e32 v16, 0xe1c, v4
	v_cndmask_b32_e64 v17, 0, v31, s[42:43]
	ds_write2_b32 v16, v3, v17 offset1:1
	v_cndmask_b32_e32 v3, 0, v34, vcc
	v_add_u32_e32 v18, 0x1224, v4
	v_cndmask_b32_e64 v19, 0, v35, s[42:43]
	v_cndmask_b32_e32 v16, 0, v32, vcc
	v_cndmask_b32_e64 v17, 0, v33, s[42:43]
	ds_write2_b32 v18, v3, v19 offset1:1
	v_cndmask_b32_e32 v18, 0, v36, vcc
	v_cndmask_b32_e64 v19, 0, v37, s[42:43]
	v_add_u32_e32 v3, 0x1000, v4
	ds_write2_b64 v3, v[16:17], v[18:19] offset0:4 offset1:133
	v_cndmask_b32_e32 v3, 0, v38, vcc
	v_add_u32_e32 v16, 0x162c, v4
	v_cndmask_b32_e64 v17, 0, v39, s[42:43]
	ds_write2_b32 v16, v3, v17 offset1:1
	v_cndmask_b32_e32 v3, 0, v42, vcc
	v_add_u32_e32 v18, 0x1a34, v4
	v_cndmask_b32_e64 v19, 0, v43, s[42:43]
	v_cndmask_b32_e32 v16, 0, v40, vcc
	v_cndmask_b32_e64 v17, 0, v41, s[42:43]
	ds_write2_b32 v18, v3, v19 offset1:1
	v_cndmask_b32_e32 v18, 0, v44, vcc
	v_cndmask_b32_e64 v19, 0, v45, s[42:43]
	v_add_u32_e32 v3, 0x1800, v4
	ds_write2_b64 v3, v[16:17], v[18:19] offset0:6 offset1:135
	v_cndmask_b32_e32 v3, 0, v46, vcc
	v_add_u32_e32 v16, 0x1e3c, v4
	v_cndmask_b32_e64 v17, 0, v47, s[42:43]
	ds_write2_b32 v16, v3, v17 offset1:1
	v_cndmask_b32_e32 v3, 0, v50, vcc
	v_add_u32_e32 v18, 0x2244, v4
	v_cndmask_b32_e64 v19, 0, v51, s[42:43]
	v_cndmask_b32_e32 v16, 0, v48, vcc
	v_cndmask_b32_e64 v17, 0, v49, s[42:43]
	ds_write2_b32 v18, v3, v19 offset1:1
	v_cndmask_b32_e32 v18, 0, v52, vcc
	v_cndmask_b32_e64 v19, 0, v53, s[42:43]
	v_add_u32_e32 v3, 0x2000, v4
	ds_write2_b64 v3, v[16:17], v[18:19] offset0:8 offset1:137
	v_cndmask_b32_e32 v3, 0, v54, vcc
	v_add_u32_e32 v16, 0x264c, v4
	v_cndmask_b32_e64 v17, 0, v55, s[42:43]
	ds_write2_b32 v16, v3, v17 offset1:1
	v_cndmask_b32_e32 v3, 0, v58, vcc
	v_add_u32_e32 v18, 0x2a54, v4
	v_cndmask_b32_e64 v19, 0, v59, s[42:43]
	v_cndmask_b32_e32 v16, 0, v56, vcc
	v_cndmask_b32_e64 v17, 0, v57, s[42:43]
	ds_write2_b32 v18, v3, v19 offset1:1
	v_cndmask_b32_e32 v18, 0, v60, vcc
	v_cndmask_b32_e64 v19, 0, v61, s[42:43]
	v_add_u32_e32 v3, 0x2800, v4
	ds_write2_b64 v3, v[16:17], v[18:19] offset0:10 offset1:139
	v_cndmask_b32_e32 v3, 0, v62, vcc
	v_add_u32_e32 v16, 0x2e5c, v4
	v_cndmask_b32_e64 v17, 0, v63, s[42:43]
	ds_write2_b32 v16, v3, v17 offset1:1
	v_cndmask_b32_e32 v3, 0, v66, vcc
	v_add_u32_e32 v18, 0x3264, v4
	v_cndmask_b32_e64 v19, 0, v67, s[42:43]
	v_cndmask_b32_e32 v16, 0, v64, vcc
	v_cndmask_b32_e64 v17, 0, v65, s[42:43]
	ds_write2_b32 v18, v3, v19 offset1:1
	v_cndmask_b32_e32 v18, 0, v68, vcc
	v_cndmask_b32_e64 v19, 0, v69, s[42:43]
	v_add_u32_e32 v3, 0x3000, v4
	ds_write2_b64 v3, v[16:17], v[18:19] offset0:12 offset1:141
	v_cndmask_b32_e32 v3, 0, v70, vcc
	v_add_u32_e32 v16, 0x366c, v4
	v_cndmask_b32_e64 v17, 0, v71, s[42:43]
	ds_write2_b32 v16, v3, v17 offset1:1
	v_cndmask_b32_e32 v3, 0, v74, vcc
	v_add_u32_e32 v18, 0x3a74, v4
	v_cndmask_b32_e64 v19, 0, v75, s[42:43]
	v_cndmask_b32_e32 v16, 0, v72, vcc
	v_cndmask_b32_e64 v17, 0, v73, s[42:43]
	ds_write2_b32 v18, v3, v19 offset1:1
	v_cndmask_b32_e32 v18, 0, v76, vcc
	v_cndmask_b32_e64 v19, 0, v77, s[42:43]
	v_add_u32_e32 v3, 0x3800, v4
	ds_write2_b64 v3, v[16:17], v[18:19] offset0:14 offset1:143
	v_cndmask_b32_e32 v3, 0, v14, vcc
	v_add_u32_e32 v14, 0x3e7c, v4
	v_cndmask_b32_e64 v15, 0, v15, s[42:43]
	ds_write2_b32 v14, v3, v15 offset1:1
	ds_read_b32 v14, v6
	ds_read_b32 v15, v6 offset:516
	ds_read_b32 v16, v6 offset:1032
	ds_read_b32 v17, v6 offset:1548
	ds_read_b32 v20, v6 offset:2064
	ds_read_b32 v21, v6 offset:2580
	ds_read_b32 v22, v6 offset:3096
	ds_read_b32 v23, v6 offset:3612
	s_lshl_b64 s[42:43], s[58:59], 1
	s_add_u32 s42, s54, s42
	s_addc_u32 s43, s55, s43
	v_mov_b32_e32 v3, v177
	v_lshl_add_u64 v[18:19], s[42:43], 0, v[2:3]
	v_or_b32_e32 v3, s33, v5
	s_ashr_i32 s6, s33, 31
	s_waitcnt lgkmcnt(0)
	v_cvt_pk_bf16_f32 v14, v14, v15
	v_cvt_pk_bf16_f32 v15, v16, v17
	v_cvt_pk_bf16_f32 v16, v20, v21
	v_cvt_pk_bf16_f32 v17, v22, v23
	s_mul_i32 s6, s50, s6
	v_mul_lo_u32 v22, s51, v3
	v_mad_u64_u32 v[20:21], s[42:43], s50, v3, 0
	v_add3_u32 v21, v21, s6, v22
	v_lshl_add_u64 v[20:21], v[20:21], 1, v[18:19]
	flat_store_dwordx4 v[20:21], v[14:17]
	ds_read_b32 v3, v6 offset:64
	ds_read_b32 v14, v6 offset:580
	ds_read_b32 v15, v6 offset:1096
	ds_read_b32 v16, v6 offset:1612
	ds_read_b32 v17, v6 offset:2128
	ds_read_b32 v20, v6 offset:2644
	ds_read_b32 v21, v6 offset:3160
	ds_read_b32 v22, v6 offset:3676
	s_waitcnt lgkmcnt(0)
	v_cvt_pk_bf16_f32 v14, v3, v14
	v_or_b32_e32 v3, s33, v7
	v_cvt_pk_bf16_f32 v15, v15, v16
	v_cvt_pk_bf16_f32 v16, v17, v20
	v_cvt_pk_bf16_f32 v17, v21, v22
	v_mul_lo_u32 v22, s51, v3
	v_mad_u64_u32 v[20:21], s[42:43], s50, v3, 0
	v_add3_u32 v21, v21, s6, v22
	v_lshl_add_u64 v[20:21], v[20:21], 1, v[18:19]
	flat_store_dwordx4 v[20:21], v[14:17]
	ds_read_b32 v3, v6 offset:128
	ds_read_b32 v14, v6 offset:644
	ds_read_b32 v15, v6 offset:1160
	ds_read_b32 v16, v6 offset:1676
	ds_read_b32 v17, v6 offset:2192
	ds_read_b32 v20, v6 offset:2708
	ds_read_b32 v21, v6 offset:3224
	ds_read_b32 v22, v6 offset:3740
	s_waitcnt lgkmcnt(0)
	v_cvt_pk_bf16_f32 v14, v3, v14
	v_or_b32_e32 v3, s33, v8
	v_cvt_pk_bf16_f32 v15, v15, v16
	v_cvt_pk_bf16_f32 v16, v17, v20
	v_cvt_pk_bf16_f32 v17, v21, v22
	v_mul_lo_u32 v22, s51, v3
	v_mad_u64_u32 v[20:21], s[42:43], s50, v3, 0
	v_add3_u32 v21, v21, s6, v22
	v_lshl_add_u64 v[20:21], v[20:21], 1, v[18:19]
	flat_store_dwordx4 v[20:21], v[14:17]
	ds_read_b32 v3, v6 offset:192
	ds_read_b32 v14, v6 offset:708
	ds_read_b32 v15, v6 offset:1224
	ds_read_b32 v16, v6 offset:1740
	ds_read_b32 v17, v6 offset:2256
	ds_read_b32 v20, v6 offset:2772
	ds_read_b32 v21, v6 offset:3288
	ds_read_b32 v22, v6 offset:3804
	s_waitcnt lgkmcnt(0)
	v_cvt_pk_bf16_f32 v14, v3, v14
	v_or_b32_e32 v3, s33, v9
	v_cvt_pk_bf16_f32 v15, v15, v16
	v_cvt_pk_bf16_f32 v16, v17, v20
	v_cvt_pk_bf16_f32 v17, v21, v22
	v_mul_lo_u32 v22, s51, v3
	v_mad_u64_u32 v[20:21], s[42:43], s50, v3, 0
	v_add3_u32 v21, v21, s6, v22
	v_lshl_add_u64 v[20:21], v[20:21], 1, v[18:19]
	flat_store_dwordx4 v[20:21], v[14:17]
	ds_read_b32 v3, v6 offset:256
	ds_read_b32 v14, v6 offset:772
	ds_read_b32 v15, v6 offset:1288
	ds_read_b32 v16, v6 offset:1804
	ds_read_b32 v17, v6 offset:2320
	ds_read_b32 v20, v6 offset:2836
	ds_read_b32 v21, v6 offset:3352
	ds_read_b32 v22, v6 offset:3868
	s_waitcnt lgkmcnt(0)
	v_cvt_pk_bf16_f32 v14, v3, v14
	v_or_b32_e32 v3, s33, v10
	v_cvt_pk_bf16_f32 v15, v15, v16
	v_cvt_pk_bf16_f32 v16, v17, v20
	v_cvt_pk_bf16_f32 v17, v21, v22
	v_mul_lo_u32 v22, s51, v3
	v_mad_u64_u32 v[20:21], s[42:43], s50, v3, 0
	v_add3_u32 v21, v21, s6, v22
	v_lshl_add_u64 v[20:21], v[20:21], 1, v[18:19]
	flat_store_dwordx4 v[20:21], v[14:17]
	ds_read_b32 v3, v6 offset:320
	ds_read_b32 v14, v6 offset:836
	ds_read_b32 v15, v6 offset:1352
	ds_read_b32 v16, v6 offset:1868
	ds_read_b32 v17, v6 offset:2384
	ds_read_b32 v20, v6 offset:2900
	ds_read_b32 v21, v6 offset:3416
	ds_read_b32 v22, v6 offset:3932
	s_waitcnt lgkmcnt(0)
	v_cvt_pk_bf16_f32 v14, v3, v14
	v_or_b32_e32 v3, s33, v11
	v_cvt_pk_bf16_f32 v15, v15, v16
	v_cvt_pk_bf16_f32 v16, v17, v20
	v_cvt_pk_bf16_f32 v17, v21, v22
	v_mul_lo_u32 v22, s51, v3
	v_mad_u64_u32 v[20:21], s[42:43], s50, v3, 0
	v_add3_u32 v21, v21, s6, v22
	v_lshl_add_u64 v[20:21], v[20:21], 1, v[18:19]
	flat_store_dwordx4 v[20:21], v[14:17]
	ds_read_b32 v3, v6 offset:384
	ds_read_b32 v14, v6 offset:900
	ds_read_b32 v15, v6 offset:1416
	ds_read_b32 v16, v6 offset:1932
	ds_read_b32 v17, v6 offset:2448
	ds_read_b32 v20, v6 offset:2964
	ds_read_b32 v21, v6 offset:3480
	ds_read_b32 v22, v6 offset:3996
	s_waitcnt lgkmcnt(0)
	v_cvt_pk_bf16_f32 v14, v3, v14
	v_or_b32_e32 v3, s33, v12
	v_cvt_pk_bf16_f32 v15, v15, v16
	v_cvt_pk_bf16_f32 v16, v17, v20
	v_cvt_pk_bf16_f32 v17, v21, v22
	v_mul_lo_u32 v22, s51, v3
	v_mad_u64_u32 v[20:21], s[42:43], s50, v3, 0
	v_add3_u32 v21, v21, s6, v22
	v_lshl_add_u64 v[20:21], v[20:21], 1, v[18:19]
	flat_store_dwordx4 v[20:21], v[14:17]
	ds_read_b32 v3, v6 offset:448
	ds_read_b32 v14, v6 offset:964
	ds_read_b32 v15, v6 offset:1480
	ds_read_b32 v16, v6 offset:1996
	ds_read_b32 v17, v6 offset:2512
	ds_read_b32 v20, v6 offset:3028
	ds_read_b32 v21, v6 offset:3544
	ds_read_b32 v22, v6 offset:4060
	s_waitcnt lgkmcnt(0)
	v_cvt_pk_bf16_f32 v14, v3, v14
	v_or_b32_e32 v3, s33, v13
	v_cvt_pk_bf16_f32 v15, v15, v16
	v_cvt_pk_bf16_f32 v16, v17, v20
	v_cvt_pk_bf16_f32 v17, v21, v22
	v_mul_lo_u32 v22, s51, v3
	v_mad_u64_u32 v[20:21], s[42:43], s50, v3, 0
	v_add3_u32 v21, v21, s6, v22
	s_addk_i32 s38, 0x780
	v_lshl_add_u64 v[18:19], v[20:21], 1, v[18:19]
	s_cmpk_gt_i32 s39, 0xfc3f
	flat_store_dwordx4 v[18:19], v[14:17]
	s_cbranch_scc1 .LBB0_697

.LBB0_797:
	s_andn2_b64 vcc, exec, s[46:47]
	v_readlane_b32 s72, v249, 50
	s_cbranch_vccnz .LBB0_908
	s_mov_b32 s41, s84
	s_cmpk_gt_i32 s88, 0x12bf
	s_cbranch_scc1 .LBB0_886
	v_readlane_b32 s0, v248, 0
	v_readlane_b32 s1, v248, 1
	s_mulk_i32 s22, 0x4100
	s_ashr_i32 s1, s0, 31
	s_add_i32 s6, s22, 0
	s_lshl_b64 s[26:27], s[0:1], 21
	s_add_u32 s8, s90, 0x2500000
	s_addc_u32 s9, s91, 0
	s_lshl_b64 s[42:43], s[0:1], 20
	s_add_u32 s76, s90, 0x2480000
	s_addc_u32 s77, s91, 0
	s_add_u32 s86, s90, 0x1eca4000
	s_addc_u32 s87, s91, 0
	s_add_u32 s92, s90, 0x6600000
	s_addc_u32 s93, s91, 0
	s_lshl_b64 s[50:51], s[0:1], 22
	s_add_u32 s94, s90, 0x2280000
	s_addc_u32 s95, s91, 0
	s_lshl_b64 s[48:49], s[0:1], 23
	s_add_u32 s96, s90, 0x1e80000
	s_addc_u32 s97, s91, 0
	s_add_u32 s38, s90, 0x1c80000
	s_addc_u32 s39, s91, 0
	s_lshl_b64 s[52:53], s[0:1], 24
	s_add_u32 s84, s90, 0x1480000
	s_addc_u32 s85, s91, 0
	v_lshlrev_b32_e32 v2, 3, v128
	s_mul_hi_i32 s80, s0, 0x2c00000
	s_mul_i32 s89, s0, 0x2c00000
	s_mul_hi_i32 s33, s0, 0x2630000
	s_mul_i32 s54, s0, 0x2630000
	s_add_u32 s0, s90, 0xf80000
	v_add_u32_e32 v4, s6, v2
	v_and_b32_e32 v2, 24, v2
	v_writelane_b32 v248, s8, 0
	s_addc_u32 s1, s91, 0
	v_mul_u32_u24_e32 v3, 0x204, v2
	v_and_b32_e32 v6, 60, v128
	v_readlane_b32 s56, v250, 41
	v_writelane_b32 v248, s9, 1
	v_add3_u32 v6, s6, v3, v6
	v_readlane_b32 s57, v250, 42
	s_add_u32 s6, s56, s26
	v_readlane_b32 s8, v249, 33
	s_addc_u32 s73, s57, s27
	v_readlane_b32 s18, v249, 43
	v_readlane_b32 s19, v249, 44
	s_add_u32 s26, s18, s42
	s_addc_u32 s27, s19, s43
	v_readlane_b32 s42, v249, 23
	v_readlane_b32 s43, v249, 24
	s_add_u32 s44, s42, s89
	v_readlane_b32 s58, v250, 43
	v_readlane_b32 s59, v250, 44
	s_addc_u32 s45, s43, s80
	v_readlane_b32 s42, v249, 19
	v_readlane_b32 s43, v249, 20
	s_add_u32 s46, s42, s50
	v_readlane_b32 s56, v249, 29
	s_addc_u32 s47, s43, s51
	v_readlane_b32 s58, v249, 31
	v_readlane_b32 s59, v249, 32
	s_add_u32 s48, s58, s48
	s_addc_u32 s49, s59, s49
	v_readlane_b32 s57, v249, 30
	s_add_u32 s50, s56, s50
	v_readlane_b32 s62, v250, 47
	s_addc_u32 s51, s57, s51
	v_readlane_b32 s60, v250, 45
	v_readlane_b32 s61, v250, 46
	v_readlane_b32 s63, v250, 48
	s_add_u32 s52, s62, s52
	s_addc_u32 s53, s63, s53
	v_readlane_b32 s56, v250, 51
	v_writelane_b32 v248, s6, 4
	v_readlane_b32 s9, v249, 34
	v_readlane_b32 s64, v250, 59
	v_lshlrev_b32_e32 v0, 1, v128
	v_lshrrev_b32_e32 v5, 2, v128
	v_readlane_b32 s8, v248, 7
	v_readlane_b32 s65, v250, 60
	s_add_u32 s54, s64, s54
	v_or_b32_e32 v1, 1, v0
	v_or_b32_e32 v7, 16, v5
	v_or_b32_e32 v8, 32, v5
	v_or_b32_e32 v9, 48, v5
	v_or_b32_e32 v10, 64, v5
	v_or_b32_e32 v11, 0x50, v5
	v_or_b32_e32 v12, 0x60, v5
	v_or_b32_e32 v13, 0x70, v5
	v_readlane_b32 s9, v248, 8
	s_addc_u32 s55, s65, s33
	v_lshlrev_b32_e32 v2, 1, v2
	s_mov_b32 s65, s88
	v_readlane_b32 s10, v249, 35
	v_readlane_b32 s11, v249, 36
	v_readlane_b32 s12, v249, 37
	v_readlane_b32 s13, v249, 38
	v_readlane_b32 s14, v249, 39
	v_readlane_b32 s15, v249, 40
	v_readlane_b32 s16, v249, 41
	v_readlane_b32 s17, v249, 42
	v_readlane_b32 s20, v249, 45
	v_readlane_b32 s21, v249, 46
	v_readlane_b32 s22, v249, 47
	v_readlane_b32 s23, v249, 48
	v_readlane_b32 s57, v250, 52
	v_readlane_b32 s58, v250, 53
	v_readlane_b32 s59, v250, 54
	v_readlane_b32 s60, v250, 55
	v_readlane_b32 s61, v250, 56
	v_readlane_b32 s62, v250, 57
	v_readlane_b32 s63, v250, 58
	v_readlane_b32 s66, v250, 61
	v_readlane_b32 s67, v250, 62
	v_readlane_b32 s68, v250, 63
	v_readlane_b32 s69, v249, 0
	v_readlane_b32 s70, v249, 1
	v_readlane_b32 s71, v249, 2
	s_waitcnt vmcnt(0)
	s_branch .LBB0_802

.LBB0_801:
	s_lshl_b32 s62, s67, 5
	s_ashr_i32 s63, s62, 31
	s_lshl_b32 s33, s66, 6
	s_mul_i32 s43, s6, s63
	s_mul_hi_u32 s66, s6, s62
	s_add_i32 s67, s66, s43
	s_mul_i32 s66, s6, s62
	s_lshl_b64 s[66:67], s[66:67], 2
	s_add_u32 s60, s60, s66
	s_addc_u32 s61, s61, s67
	s_ashr_i32 s43, s42, 31
	s_lshl_b64 s[42:43], s[42:43], 2
	s_add_u32 s42, s60, s42
	s_addc_u32 s43, s61, s43
	v_lshlrev_b32_e32 v176, 2, v0
	v_lshl_add_u64 v[14:15], s[42:43], 0, v[176:177]
	global_load_dwordx2 v[16:17], v176, s[42:43] nt
	s_lshl_b32 s42, s6, 1
	s_mov_b32 s43, s7
	v_lshl_add_u64 v[20:21], s[42:43], 2, v[14:15]
	s_mul_i32 s42, s6, 3
	v_lshl_add_u64 v[22:23], s[42:43], 2, v[14:15]
	s_lshl_b32 s42, s6, 2
	v_lshl_add_u64 v[24:25], s[42:43], 2, v[14:15]
	s_mul_i32 s42, s6, 5
	v_lshl_add_u64 v[26:27], s[42:43], 2, v[14:15]
	s_mul_i32 s42, s6, 6
	v_lshl_add_u64 v[28:29], s[42:43], 2, v[14:15]
	s_mul_i32 s42, s6, 7
	v_lshl_add_u64 v[30:31], s[42:43], 2, v[14:15]
	s_lshl_b32 s42, s6, 3
	v_lshl_add_u64 v[32:33], s[42:43], 2, v[14:15]
	s_mul_i32 s42, s6, 9
	v_lshl_add_u64 v[34:35], s[42:43], 2, v[14:15]
	s_mul_i32 s42, s6, 10
	v_lshl_add_u64 v[18:19], s[6:7], 2, v[14:15]
	v_lshl_add_u64 v[36:37], s[42:43], 2, v[14:15]
	s_mul_i32 s42, s6, 11
	global_load_dwordx2 v[18:19], v[18:19], off nt
	s_nop 0
	global_load_dwordx2 v[20:21], v[20:21], off nt
	s_nop 0
	global_load_dwordx2 v[22:23], v[22:23], off nt
	s_nop 0
	global_load_dwordx2 v[24:25], v[24:25], off nt
	v_lshl_add_u64 v[38:39], s[42:43], 2, v[14:15]
	s_mul_i32 s42, s6, 12
	v_lshl_add_u64 v[40:41], s[42:43], 2, v[14:15]
	s_mul_i32 s42, s6, 13
	v_lshl_add_u64 v[42:43], s[42:43], 2, v[14:15]
	s_mul_i32 s42, s6, 14
	global_load_dwordx2 v[26:27], v[26:27], off nt
	s_nop 0
	global_load_dwordx2 v[28:29], v[28:29], off nt
	s_nop 0
	global_load_dwordx2 v[30:31], v[30:31], off nt
	s_nop 0
	global_load_dwordx2 v[32:33], v[32:33], off nt
	v_lshl_add_u64 v[44:45], s[42:43], 2, v[14:15]
	s_mul_i32 s42, s6, 15
	v_lshl_add_u64 v[46:47], s[42:43], 2, v[14:15]
	s_lshl_b32 s42, s6, 4
	v_lshl_add_u64 v[48:49], s[42:43], 2, v[14:15]
	s_mul_i32 s42, s6, 17
	global_load_dwordx2 v[34:35], v[34:35], off nt
	s_nop 0
	global_load_dwordx2 v[36:37], v[36:37], off nt
	s_nop 0
	global_load_dwordx2 v[38:39], v[38:39], off nt
	s_nop 0
	global_load_dwordx2 v[40:41], v[40:41], off nt
	v_lshl_add_u64 v[50:51], s[42:43], 2, v[14:15]
	s_mul_i32 s42, s6, 18
	v_lshl_add_u64 v[52:53], s[42:43], 2, v[14:15]
	s_mul_i32 s42, s6, 19
	v_lshl_add_u64 v[54:55], s[42:43], 2, v[14:15]
	s_mul_i32 s42, s6, 20
	global_load_dwordx2 v[42:43], v[42:43], off nt
	s_nop 0
	global_load_dwordx2 v[44:45], v[44:45], off nt
	s_nop 0
	global_load_dwordx2 v[46:47], v[46:47], off nt
	s_nop 0
	global_load_dwordx2 v[48:49], v[48:49], off nt
	v_lshl_add_u64 v[56:57], s[42:43], 2, v[14:15]
	s_mul_i32 s42, s6, 21
	v_lshl_add_u64 v[58:59], s[42:43], 2, v[14:15]
	s_mul_i32 s42, s6, 22
	v_lshl_add_u64 v[60:61], s[42:43], 2, v[14:15]
	s_mul_i32 s42, s6, 23
	global_load_dwordx2 v[50:51], v[50:51], off nt
	s_nop 0
	global_load_dwordx2 v[52:53], v[52:53], off nt
	s_nop 0
	global_load_dwordx2 v[54:55], v[54:55], off nt
	s_nop 0
	global_load_dwordx2 v[56:57], v[56:57], off nt
	v_lshl_add_u64 v[62:63], s[42:43], 2, v[14:15]
	s_mul_i32 s42, s6, 24
	s_waitcnt lgkmcnt(0)
	v_lshl_add_u64 v[64:65], s[42:43], 2, v[14:15]
	s_mul_i32 s42, s6, 25
	v_lshl_add_u64 v[66:67], s[42:43], 2, v[14:15]
	s_mul_i32 s42, s6, 26
	global_load_dwordx2 v[58:59], v[58:59], off nt
	s_nop 0
	global_load_dwordx2 v[60:61], v[60:61], off nt
	s_nop 0
	global_load_dwordx2 v[62:63], v[62:63], off nt
	s_nop 0
	global_load_dwordx2 v[64:65], v[64:65], off nt
	v_lshl_add_u64 v[68:69], s[42:43], 2, v[14:15]
	s_mul_i32 s42, s6, 27
	v_lshl_add_u64 v[70:71], s[42:43], 2, v[14:15]
	s_mul_i32 s42, s6, 28
	v_lshl_add_u64 v[72:73], s[42:43], 2, v[14:15]
	s_mul_i32 s42, s6, 29
	global_load_dwordx2 v[66:67], v[66:67], off nt
	s_nop 0
	global_load_dwordx2 v[68:69], v[68:69], off nt
	s_nop 0
	global_load_dwordx2 v[70:71], v[70:71], off nt
	s_nop 0
	global_load_dwordx2 v[72:73], v[72:73], off nt
	v_lshl_add_u64 v[74:75], s[42:43], 2, v[14:15]
	s_mul_i32 s42, s6, 30
	s_mul_i32 s6, s6, 31
	v_lshl_add_u64 v[76:77], s[42:43], 2, v[14:15]
	v_lshl_add_u64 v[14:15], s[6:7], 2, v[14:15]
	global_load_dwordx2 v[74:75], v[74:75], off nt
	s_nop 0
	global_load_dwordx2 v[76:77], v[76:77], off nt
	s_nop 0
	global_load_dwordx2 v[14:15], v[14:15], off nt
	s_waitcnt vmcnt(23)
	v_cmp_gt_u32_e32 vcc, s68, v0
	v_cmp_gt_u32_e64 s[42:43], s68, v1
	s_nop 0
	v_cndmask_b32_e32 v16, 0, v16, vcc
	v_cndmask_b32_e64 v17, 0, v17, s[42:43]
	v_cndmask_b32_e32 v3, 0, v18, vcc
	v_cndmask_b32_e64 v18, 0, v19, s[42:43]
	ds_write2_b32 v4, v3, v18 offset0:129 offset1:130
	v_cndmask_b32_e32 v18, 0, v20, vcc
	v_cndmask_b32_e64 v19, 0, v21, s[42:43]
	ds_write2_b64 v4, v[16:17], v[18:19] offset1:129
	v_cndmask_b32_e32 v3, 0, v22, vcc
	v_add_u32_e32 v16, 0x60c, v4
	v_cndmask_b32_e64 v17, 0, v23, s[42:43]
	ds_write2_b32 v16, v3, v17 offset1:1
	v_cndmask_b32_e32 v3, 0, v26, vcc
	v_add_u32_e32 v18, 0xa14, v4
	v_cndmask_b32_e64 v19, 0, v27, s[42:43]
	v_cndmask_b32_e32 v16, 0, v24, vcc
	v_cndmask_b32_e64 v17, 0, v25, s[42:43]
	ds_write2_b32 v18, v3, v19 offset1:1
	v_cndmask_b32_e32 v18, 0, v28, vcc
	v_cndmask_b32_e64 v19, 0, v29, s[42:43]
	v_add_u32_e32 v3, 0x800, v4
	ds_write2_b64 v3, v[16:17], v[18:19] offset0:2 offset1:131
	v_cndmask_b32_e32 v3, 0, v30, vcc
	v_add_u32_e32 v16, 0xe1c, v4
	v_cndmask_b32_e64 v17, 0, v31, s[42:43]
	ds_write2_b32 v16, v3, v17 offset1:1
	s_waitcnt vmcnt(22)
	v_cndmask_b32_e32 v3, 0, v34, vcc
	v_add_u32_e32 v18, 0x1224, v4
	v_cndmask_b32_e64 v19, 0, v35, s[42:43]
	v_cndmask_b32_e32 v16, 0, v32, vcc
	v_cndmask_b32_e64 v17, 0, v33, s[42:43]
	ds_write2_b32 v18, v3, v19 offset1:1
	s_waitcnt vmcnt(21)
	v_cndmask_b32_e32 v18, 0, v36, vcc
	v_cndmask_b32_e64 v19, 0, v37, s[42:43]
	v_add_u32_e32 v3, 0x1000, v4
	ds_write2_b64 v3, v[16:17], v[18:19] offset0:4 offset1:133
	s_waitcnt vmcnt(20)
	v_cndmask_b32_e32 v3, 0, v38, vcc
	v_add_u32_e32 v16, 0x162c, v4
	v_cndmask_b32_e64 v17, 0, v39, s[42:43]
	ds_write2_b32 v16, v3, v17 offset1:1
	s_waitcnt vmcnt(18)
	v_cndmask_b32_e32 v3, 0, v42, vcc
	v_add_u32_e32 v18, 0x1a34, v4
	v_cndmask_b32_e64 v19, 0, v43, s[42:43]
	v_cndmask_b32_e32 v16, 0, v40, vcc
	v_cndmask_b32_e64 v17, 0, v41, s[42:43]
	ds_write2_b32 v18, v3, v19 offset1:1
	s_waitcnt vmcnt(17)
	v_cndmask_b32_e32 v18, 0, v44, vcc
	v_cndmask_b32_e64 v19, 0, v45, s[42:43]
	v_add_u32_e32 v3, 0x1800, v4
	ds_write2_b64 v3, v[16:17], v[18:19] offset0:6 offset1:135
	s_waitcnt vmcnt(16)
	v_cndmask_b32_e32 v3, 0, v46, vcc
	v_add_u32_e32 v16, 0x1e3c, v4
	v_cndmask_b32_e64 v17, 0, v47, s[42:43]
	ds_write2_b32 v16, v3, v17 offset1:1
	s_waitcnt vmcnt(14)
	v_cndmask_b32_e32 v3, 0, v50, vcc
	v_add_u32_e32 v18, 0x2244, v4
	v_cndmask_b32_e64 v19, 0, v51, s[42:43]
	v_cndmask_b32_e32 v16, 0, v48, vcc
	v_cndmask_b32_e64 v17, 0, v49, s[42:43]
	ds_write2_b32 v18, v3, v19 offset1:1
	s_waitcnt vmcnt(13)
	v_cndmask_b32_e32 v18, 0, v52, vcc
	v_cndmask_b32_e64 v19, 0, v53, s[42:43]
	v_add_u32_e32 v3, 0x2000, v4
	ds_write2_b64 v3, v[16:17], v[18:19] offset0:8 offset1:137
	s_waitcnt vmcnt(12)
	v_cndmask_b32_e32 v3, 0, v54, vcc
	v_add_u32_e32 v16, 0x264c, v4
	v_cndmask_b32_e64 v17, 0, v55, s[42:43]
	ds_write2_b32 v16, v3, v17 offset1:1
	s_waitcnt vmcnt(10)
	v_cndmask_b32_e32 v3, 0, v58, vcc
	v_add_u32_e32 v18, 0x2a54, v4
	v_cndmask_b32_e64 v19, 0, v59, s[42:43]
	v_cndmask_b32_e32 v16, 0, v56, vcc
	v_cndmask_b32_e64 v17, 0, v57, s[42:43]
	ds_write2_b32 v18, v3, v19 offset1:1
	s_waitcnt vmcnt(9)
	v_cndmask_b32_e32 v18, 0, v60, vcc
	v_cndmask_b32_e64 v19, 0, v61, s[42:43]
	v_add_u32_e32 v3, 0x2800, v4
	ds_write2_b64 v3, v[16:17], v[18:19] offset0:10 offset1:139
	s_waitcnt vmcnt(8)
	v_cndmask_b32_e32 v3, 0, v62, vcc
	v_add_u32_e32 v16, 0x2e5c, v4
	v_cndmask_b32_e64 v17, 0, v63, s[42:43]
	ds_write2_b32 v16, v3, v17 offset1:1
	s_waitcnt vmcnt(6)
	v_cndmask_b32_e32 v3, 0, v66, vcc
	v_add_u32_e32 v18, 0x3264, v4
	v_cndmask_b32_e64 v19, 0, v67, s[42:43]
	v_cndmask_b32_e32 v16, 0, v64, vcc
	v_cndmask_b32_e64 v17, 0, v65, s[42:43]
	ds_write2_b32 v18, v3, v19 offset1:1
	s_waitcnt vmcnt(5)
	v_cndmask_b32_e32 v18, 0, v68, vcc
	v_cndmask_b32_e64 v19, 0, v69, s[42:43]
	v_add_u32_e32 v3, 0x3000, v4
	ds_write2_b64 v3, v[16:17], v[18:19] offset0:12 offset1:141
	s_waitcnt vmcnt(4)
	v_cndmask_b32_e32 v3, 0, v70, vcc
	v_add_u32_e32 v16, 0x366c, v4
	v_cndmask_b32_e64 v17, 0, v71, s[42:43]
	ds_write2_b32 v16, v3, v17 offset1:1
	s_waitcnt vmcnt(2)
	v_cndmask_b32_e32 v3, 0, v74, vcc
	v_add_u32_e32 v18, 0x3a74, v4
	v_cndmask_b32_e64 v19, 0, v75, s[42:43]
	v_cndmask_b32_e32 v16, 0, v72, vcc
	v_cndmask_b32_e64 v17, 0, v73, s[42:43]
	ds_write2_b32 v18, v3, v19 offset1:1
	s_waitcnt vmcnt(1)
	v_cndmask_b32_e32 v18, 0, v76, vcc
	v_cndmask_b32_e64 v19, 0, v77, s[42:43]
	v_add_u32_e32 v3, 0x3800, v4
	ds_write2_b64 v3, v[16:17], v[18:19] offset0:14 offset1:143
	s_waitcnt vmcnt(0)
	v_cndmask_b32_e32 v3, 0, v14, vcc
	v_add_u32_e32 v14, 0x3e7c, v4
	v_cndmask_b32_e64 v15, 0, v15, s[42:43]
	ds_write2_b32 v14, v3, v15 offset1:1
	ds_read_b32 v14, v6
	ds_read_b32 v15, v6 offset:516
	ds_read_b32 v16, v6 offset:1032
	ds_read_b32 v17, v6 offset:1548
	ds_read_b32 v20, v6 offset:2064
	ds_read_b32 v21, v6 offset:2580
	ds_read_b32 v22, v6 offset:3096
	ds_read_b32 v23, v6 offset:3612
	s_lshl_b64 s[42:43], s[62:63], 1
	s_add_u32 s42, s58, s42
	s_addc_u32 s43, s59, s43
	v_mov_b32_e32 v3, v177
	v_lshl_add_u64 v[18:19], s[42:43], 0, v[2:3]
	v_or_b32_e32 v3, s33, v5
	s_ashr_i32 s6, s33, 31
	s_waitcnt lgkmcnt(6)
	v_cvt_pk_bf16_f32 v14, v14, v15
	s_waitcnt lgkmcnt(4)
	v_cvt_pk_bf16_f32 v15, v16, v17
	s_waitcnt lgkmcnt(2)
	v_cvt_pk_bf16_f32 v16, v20, v21
	s_waitcnt lgkmcnt(0)
	v_cvt_pk_bf16_f32 v17, v22, v23
	s_mul_i32 s6, s56, s6
	v_mul_lo_u32 v22, s57, v3
	v_mad_u64_u32 v[20:21], s[42:43], s56, v3, 0
	v_add3_u32 v21, v21, s6, v22
	v_lshl_add_u64 v[20:21], v[20:21], 1, v[18:19]
	flat_store_dwordx4 v[20:21], v[14:17]
	ds_read_b32 v3, v6 offset:64
	ds_read_b32 v14, v6 offset:580
	ds_read_b32 v15, v6 offset:1096
	ds_read_b32 v16, v6 offset:1612
	ds_read_b32 v17, v6 offset:2128
	ds_read_b32 v20, v6 offset:2644
	ds_read_b32 v21, v6 offset:3160
	ds_read_b32 v22, v6 offset:3676
	s_waitcnt lgkmcnt(0)
	v_cvt_pk_bf16_f32 v14, v3, v14
	v_or_b32_e32 v3, s33, v7
	v_cvt_pk_bf16_f32 v15, v15, v16
	v_cvt_pk_bf16_f32 v16, v17, v20
	v_cvt_pk_bf16_f32 v17, v21, v22
	v_mul_lo_u32 v22, s57, v3
	v_mad_u64_u32 v[20:21], s[42:43], s56, v3, 0
	v_add3_u32 v21, v21, s6, v22
	v_lshl_add_u64 v[20:21], v[20:21], 1, v[18:19]
	flat_store_dwordx4 v[20:21], v[14:17]
	ds_read_b32 v3, v6 offset:128
	ds_read_b32 v14, v6 offset:644
	ds_read_b32 v15, v6 offset:1160
	ds_read_b32 v16, v6 offset:1676
	ds_read_b32 v17, v6 offset:2192
	ds_read_b32 v20, v6 offset:2708
	ds_read_b32 v21, v6 offset:3224
	ds_read_b32 v22, v6 offset:3740
	s_waitcnt lgkmcnt(0)
	v_cvt_pk_bf16_f32 v14, v3, v14
	v_or_b32_e32 v3, s33, v8
	v_cvt_pk_bf16_f32 v15, v15, v16
	v_cvt_pk_bf16_f32 v16, v17, v20
	v_cvt_pk_bf16_f32 v17, v21, v22
	v_mul_lo_u32 v22, s57, v3
	v_mad_u64_u32 v[20:21], s[42:43], s56, v3, 0
	v_add3_u32 v21, v21, s6, v22
	v_lshl_add_u64 v[20:21], v[20:21], 1, v[18:19]
	flat_store_dwordx4 v[20:21], v[14:17]
	ds_read_b32 v3, v6 offset:192
	ds_read_b32 v14, v6 offset:708
	ds_read_b32 v15, v6 offset:1224
	ds_read_b32 v16, v6 offset:1740
	ds_read_b32 v17, v6 offset:2256
	ds_read_b32 v20, v6 offset:2772
	ds_read_b32 v21, v6 offset:3288
	ds_read_b32 v22, v6 offset:3804
	s_waitcnt lgkmcnt(0)
	v_cvt_pk_bf16_f32 v14, v3, v14
	v_or_b32_e32 v3, s33, v9
	v_cvt_pk_bf16_f32 v15, v15, v16
	v_cvt_pk_bf16_f32 v16, v17, v20
	v_cvt_pk_bf16_f32 v17, v21, v22
	v_mul_lo_u32 v22, s57, v3
	v_mad_u64_u32 v[20:21], s[42:43], s56, v3, 0
	v_add3_u32 v21, v21, s6, v22
	v_lshl_add_u64 v[20:21], v[20:21], 1, v[18:19]
	flat_store_dwordx4 v[20:21], v[14:17]
	ds_read_b32 v3, v6 offset:256
	ds_read_b32 v14, v6 offset:772
	ds_read_b32 v15, v6 offset:1288
	ds_read_b32 v16, v6 offset:1804
	ds_read_b32 v17, v6 offset:2320
	ds_read_b32 v20, v6 offset:2836
	ds_read_b32 v21, v6 offset:3352
	ds_read_b32 v22, v6 offset:3868
	s_waitcnt lgkmcnt(0)
	v_cvt_pk_bf16_f32 v14, v3, v14
	v_or_b32_e32 v3, s33, v10
	v_cvt_pk_bf16_f32 v15, v15, v16
	v_cvt_pk_bf16_f32 v16, v17, v20
	v_cvt_pk_bf16_f32 v17, v21, v22
	v_mul_lo_u32 v22, s57, v3
	v_mad_u64_u32 v[20:21], s[42:43], s56, v3, 0
	v_add3_u32 v21, v21, s6, v22
	v_lshl_add_u64 v[20:21], v[20:21], 1, v[18:19]
	flat_store_dwordx4 v[20:21], v[14:17]
	ds_read_b32 v3, v6 offset:320
	ds_read_b32 v14, v6 offset:836
	ds_read_b32 v15, v6 offset:1352
	ds_read_b32 v16, v6 offset:1868
	ds_read_b32 v17, v6 offset:2384
	ds_read_b32 v20, v6 offset:2900
	ds_read_b32 v21, v6 offset:3416
	ds_read_b32 v22, v6 offset:3932
	s_waitcnt lgkmcnt(0)
	v_cvt_pk_bf16_f32 v14, v3, v14
	v_or_b32_e32 v3, s33, v11
	v_cvt_pk_bf16_f32 v15, v15, v16
	v_cvt_pk_bf16_f32 v16, v17, v20
	v_cvt_pk_bf16_f32 v17, v21, v22
	v_mul_lo_u32 v22, s57, v3
	v_mad_u64_u32 v[20:21], s[42:43], s56, v3, 0
	v_add3_u32 v21, v21, s6, v22
	v_lshl_add_u64 v[20:21], v[20:21], 1, v[18:19]
	flat_store_dwordx4 v[20:21], v[14:17]
	ds_read_b32 v3, v6 offset:384
	ds_read_b32 v14, v6 offset:900
	ds_read_b32 v15, v6 offset:1416
	ds_read_b32 v16, v6 offset:1932
	ds_read_b32 v17, v6 offset:2448
	ds_read_b32 v20, v6 offset:2964
	ds_read_b32 v21, v6 offset:3480
	ds_read_b32 v22, v6 offset:3996
	s_waitcnt lgkmcnt(0)
	v_cvt_pk_bf16_f32 v14, v3, v14
	v_or_b32_e32 v3, s33, v12
	v_cvt_pk_bf16_f32 v15, v15, v16
	v_cvt_pk_bf16_f32 v16, v17, v20
	v_cvt_pk_bf16_f32 v17, v21, v22
	v_mul_lo_u32 v22, s57, v3
	v_mad_u64_u32 v[20:21], s[42:43], s56, v3, 0
	v_add3_u32 v21, v21, s6, v22
	v_lshl_add_u64 v[20:21], v[20:21], 1, v[18:19]
	flat_store_dwordx4 v[20:21], v[14:17]
	ds_read_b32 v3, v6 offset:448
	ds_read_b32 v14, v6 offset:964
	ds_read_b32 v15, v6 offset:1480
	ds_read_b32 v16, v6 offset:1996
	ds_read_b32 v17, v6 offset:2512
	ds_read_b32 v20, v6 offset:3028
	ds_read_b32 v21, v6 offset:3544
	ds_read_b32 v22, v6 offset:4060
	s_waitcnt lgkmcnt(0)
	v_cvt_pk_bf16_f32 v14, v3, v14
	v_or_b32_e32 v3, s33, v13
	v_cvt_pk_bf16_f32 v15, v15, v16
	v_cvt_pk_bf16_f32 v16, v17, v20
	v_cvt_pk_bf16_f32 v17, v21, v22
	v_mul_lo_u32 v22, s57, v3
	v_mad_u64_u32 v[20:21], s[42:43], s56, v3, 0
	v_add3_u32 v21, v21, s6, v22
	s_add_i32 s65, s65, s36
	v_lshl_add_u64 v[18:19], v[20:21], 1, v[18:19]
	s_cmpk_lt_i32 s65, 0x12c0
	flat_store_dwordx4 v[18:19], v[14:17]
	s_cbranch_scc0 .LBB0_886
